# weight transpose item loops unrolled with a second register set: all 32 row loads of an item in flight before the first LDS write
# speedup vs baseline: 1.0197x; 1.0011x over previous
;     ...
; #pragma unroll 8
;     for (int i = 0; i < 32; ++i) { const int kk = 2 * i + (lane >> 5); scr[kk * 33 + (lane & 31)] = W[(size_t)(k0 + kk) * N + n0 + (lane & 31)]; }
; __device__ __forceinline__ void phase_convert(const Args& a, LAS unsigned char* lds) {
;     ...
;         if (r < 32) { transpose_item(a.in[I_W2] + (size_t)l * 64 * DA, 64, DA, (bf16*)(ws + WS_W2T) + (size_t)l * DA * 64, 1 << 30, scr, r, lane); continue; } r -= 32;
.LBB0_475:
	s_lshl_b32 s45, s3, 1
	s_lshl_b32 s46, s43, 1
	v_or_b32_e32 v0, s46, v2
	s_add_i32 s48, s45, 4
	s_add_i32 s49, s46, 4
	v_mov_b32_e32 v23, v1
	s_add_i32 s50, s45, 8
	s_add_i32 s51, s46, 8
	s_add_i32 s53, s46, 12
	s_add_i32 s55, s46, 16
	s_add_i32 s56, s45, 20
	s_add_i32 s57, s46, 20
	s_add_i32 s58, s45, 24
	s_add_i32 s59, s46, 24
	s_add_i32 s60, s46, 28
	v_lshlrev_b64 v[40:41], 12, v[0:1]
	v_mad_u64_u32 v[42:43], s[46:47], v0, s85, v[6:7]
	v_or_b32_e32 v22, s48, v3
	v_or_b32_e32 v0, s49, v2
	v_mov_b32_e32 v17, v1
	v_mov_b32_e32 v25, v1
	v_mov_b32_e32 v31, v1
	v_mov_b32_e32 v33, v1
	v_or_b32_e32 v16, s45, v3
	s_add_i32 s52, s45, 12
	s_add_i32 s54, s45, 16
	s_add_i32 s45, s45, 28
	v_or_b32_e32 v24, s50, v3
	v_or_b32_e32 v30, s56, v3
	v_or_b32_e32 v32, s58, v3
	v_lshlrev_b64 v[44:45], 12, v[22:23]
	v_lshlrev_b64 v[46:47], 12, v[0:1]
	v_mad_u64_u32 v[48:49], s[46:47], v0, s85, v[6:7]
	v_or_b32_e32 v0, s51, v2
	v_mov_b32_e32 v27, v1
	v_mov_b32_e32 v29, v1
	v_mov_b32_e32 v35, v1
	v_lshlrev_b64 v[36:37], 12, v[16:17]
	v_or_b32_e32 v26, s52, v3
	v_or_b32_e32 v28, s54, v3
	v_or_b32_e32 v34, s45, v3
	v_lshl_add_u64 v[40:41], v[14:15], 0, v[40:41]
	v_lshlrev_b64 v[50:51], 12, v[24:25]
	v_lshlrev_b64 v[56:57], 12, v[30:31]
	v_lshlrev_b64 v[58:59], 12, v[32:33]
	v_lshl_add_u64 v[44:45], v[14:15], 0, v[44:45]
	v_lshlrev_b64 v[62:63], 12, v[0:1]
	v_mad_u64_u32 v[64:65], s[46:47], v0, s85, v[6:7]
	v_or_b32_e32 v0, s53, v2
	v_lshl_add_u64 v[36:37], v[14:15], 0, v[36:37]
	v_lshlrev_b64 v[52:53], 12, v[26:27]
	v_lshlrev_b64 v[54:55], 12, v[28:29]
	v_lshlrev_b64 v[60:61], 12, v[34:35]
	v_lshl_add_u64 v[46:47], v[14:15], 0, v[46:47]
	v_lshl_add_u64 v[50:51], v[14:15], 0, v[50:51]
	v_lshl_add_u64 v[56:57], v[14:15], 0, v[56:57]
	v_lshl_add_u64 v[58:59], v[14:15], 0, v[58:59]
	global_load_dword v5, v[40:41], off
	global_load_dword v21, v[36:37], off
	global_load_dword v39, v[46:47], off
	global_load_dword v43, v[44:45], off
	v_lshlrev_b64 v[40:41], 12, v[0:1]
	v_mad_u64_u32 v[44:45], s[46:47], v0, s85, v[6:7]
	v_or_b32_e32 v0, s55, v2
	v_lshl_add_u64 v[52:53], v[14:15], 0, v[52:53]
	v_lshl_add_u64 v[54:55], v[14:15], 0, v[54:55]
	v_lshl_add_u64 v[60:61], v[14:15], 0, v[60:61]
	v_lshl_add_u64 v[36:37], v[14:15], 0, v[62:63]
	global_load_dword v45, v[50:51], off
	global_load_dword v49, v[52:53], off
	global_load_dword v62, v[54:55], off
	s_nop 0
	global_load_dword v56, v[56:57], off
	s_nop 0
	global_load_dword v57, v[58:59], off
	s_nop 0
	global_load_dword v58, v[60:61], off
	v_lshl_add_u64 v[40:41], v[14:15], 0, v[40:41]
	v_lshlrev_b64 v[46:47], 12, v[0:1]
	v_mad_u64_u32 v[50:51], s[46:47], v0, s85, v[6:7]
	v_or_b32_e32 v0, s57, v2
	global_load_dword v51, v[36:37], off
	global_load_dword v59, v[40:41], off
	v_lshl_add_u64 v[36:37], v[14:15], 0, v[46:47]
	v_lshlrev_b64 v[40:41], 12, v[0:1]
	v_mad_u64_u32 v[46:47], s[46:47], v0, s85, v[6:7]
	v_or_b32_e32 v0, s59, v2
	v_mad_u64_u32 v[54:55], s[46:47], v0, s85, v[6:7]
	v_lshl_add_u64 v[40:41], v[14:15], 0, v[40:41]
	global_load_dword v47, v[36:37], off
	global_load_dword v55, v[40:41], off
	v_lshlrev_b64 v[52:53], 12, v[0:1]
	v_or_b32_e32 v0, s60, v2
	v_lshl_add_u64 v[36:37], v[14:15], 0, v[52:53]
	v_lshlrev_b64 v[40:41], 12, v[0:1]
	global_load_dword v52, v[36:37], off
	v_lshl_add_u64 v[36:37], v[14:15], 0, v[40:41]
	global_load_dword v40, v[36:37], off
	s_add_i32 s43, s43, 16
	s_add_i32 s3, s3, 16
	s_add_i32 s44, s44, -16
	s_cmp_lg_u32 s44, 0
	v_mov_b32_e32 v95, 0
	s_lshl_b32 s45, s3, 1
	s_lshl_b32 s46, s43, 1
	v_or_b32_e32 v94, s46, v2
	s_add_i32 s48, s45, 4
	s_add_i32 s49, s46, 4
	v_mov_b32_e32 v103, v95
	s_add_i32 s50, s45, 8
	s_add_i32 s51, s46, 8
	s_add_i32 s53, s46, 12
	s_add_i32 s55, s46, 16
	s_add_i32 s56, s45, 20
	s_add_i32 s57, s46, 20
	s_add_i32 s58, s45, 24
	s_add_i32 s59, s46, 24
	s_add_i32 s60, s46, 28
	v_lshlrev_b64 v[120:121], 12, v[94:95]
	v_mad_u64_u32 v[122:123], s[46:47], v94, s85, v[6:7]
	v_or_b32_e32 v102, s48, v3
	v_or_b32_e32 v94, s49, v2
	v_mov_b32_e32 v99, v95
	v_mov_b32_e32 v105, v95
	v_mov_b32_e32 v111, v95
	v_mov_b32_e32 v113, v95
	v_or_b32_e32 v98, s45, v3
	s_add_i32 s52, s45, 12
	s_add_i32 s54, s45, 16
	s_add_i32 s45, s45, 28
	v_or_b32_e32 v104, s50, v3
	v_or_b32_e32 v110, s56, v3
	v_or_b32_e32 v112, s58, v3
	v_lshlrev_b64 v[124:125], 12, v[102:103]
	v_lshlrev_b64 v[126:127], 12, v[94:95]
	v_mad_u64_u32 v[128:129], s[46:47], v94, s85, v[6:7]
	v_or_b32_e32 v94, s51, v2
	v_mov_b32_e32 v107, v95
	v_mov_b32_e32 v109, v95
	v_mov_b32_e32 v115, v95
	v_lshlrev_b64 v[116:117], 12, v[98:99]
	v_or_b32_e32 v106, s52, v3
	v_or_b32_e32 v108, s54, v3
	v_or_b32_e32 v114, s45, v3
	v_lshl_add_u64 v[120:121], v[14:15], 0, v[120:121]
	v_lshlrev_b64 v[130:131], 12, v[104:105]
	v_lshlrev_b64 v[136:137], 12, v[110:111]
	v_lshlrev_b64 v[150:151], 12, v[112:113]
	v_lshl_add_u64 v[124:125], v[14:15], 0, v[124:125]
	v_lshlrev_b64 v[154:155], 12, v[94:95]
	v_mad_u64_u32 v[156:157], s[46:47], v94, s85, v[6:7]
	v_or_b32_e32 v94, s53, v2
	v_lshl_add_u64 v[116:117], v[14:15], 0, v[116:117]
	v_lshlrev_b64 v[132:133], 12, v[106:107]
	v_lshlrev_b64 v[134:135], 12, v[108:109]
	v_lshlrev_b64 v[152:153], 12, v[114:115]
	v_lshl_add_u64 v[126:127], v[14:15], 0, v[126:127]
	v_lshl_add_u64 v[130:131], v[14:15], 0, v[130:131]
	v_lshl_add_u64 v[136:137], v[14:15], 0, v[136:137]
	v_lshl_add_u64 v[150:151], v[14:15], 0, v[150:151]
	global_load_dword v97, v[120:121], off
	global_load_dword v101, v[116:117], off
	global_load_dword v119, v[126:127], off
	global_load_dword v123, v[124:125], off
	v_lshlrev_b64 v[120:121], 12, v[94:95]
	v_mad_u64_u32 v[124:125], s[46:47], v94, s85, v[6:7]
	v_or_b32_e32 v94, s55, v2
; __device__ __forceinline__ unsigned cvt_pk_bf16(float lo, float hi) { unsigned r; asm volatile("v_cvt_pk_bf16_f32 %0, %1, %2" : "=v"(r) : "v"(lo), "v"(hi)); return r; }
; #define LAS __attribute__((address_space(3)))
; #define LDS_WAIT() asm volatile("s_waitcnt lgkmcnt(0)" ::: "memory")
;     ...
;     for (int i = 0; i < 32; ++i) { const int kk = 2 * i + (lane >> 5); scr[kk * 33 + (lane & 31)] = W[(size_t)(k0 + kk) * N + n0 + (lane & 31)]; }
;     LDS_WAIT(); asm volatile("" ::: "memory");
;     const int c = lane & 7;
; #pragma unroll
;     for (int j = 0; j < 4; ++j) { const int n = (lane >> 3) + 8 * j; const LAS float* s = scr + (8 * c) * 33 + n;
;         u32x4 o; o.x = cvt_pk_bf16(s[0 * 33], s[1 * 33]); o.y = cvt_pk_bf16(s[2 * 33], s[3 * 33]); o.z = cvt_pk_bf16(s[4 * 33], s[5 * 33]); o.w = cvt_pk_bf16(s[6 * 33], s[7 * 33]);
;         *(u32x4*)(WT + (size_t)(dn0 + n) * ldo + koff + k0 + 8 * c) = o; }
;     LDS_WAIT(); asm volatile("" ::: "memory");
; __device__ __forceinline__ void phase_convert(const Args& a, LAS unsigned char* lds) {
;     ...
;         if (r < 32) { transpose_item(a.in[I_W2] + (size_t)l * 64 * DA, 64, DA, (bf16*)(ws + WS_W2T) + (size_t)l * DA * 64, 1 << 30, scr, r, lane); continue; } r -= 32;
	v_lshl_add_u64 v[132:133], v[14:15], 0, v[132:133]
	v_lshl_add_u64 v[134:135], v[14:15], 0, v[134:135]
	v_lshl_add_u64 v[152:153], v[14:15], 0, v[152:153]
	v_lshl_add_u64 v[116:117], v[14:15], 0, v[154:155]
	global_load_dword v125, v[130:131], off
	global_load_dword v129, v[132:133], off
	global_load_dword v154, v[134:135], off
	s_nop 0
	global_load_dword v136, v[136:137], off
	s_nop 0
	global_load_dword v137, v[150:151], off
	s_nop 0
	global_load_dword v150, v[152:153], off
	v_lshl_add_u64 v[120:121], v[14:15], 0, v[120:121]
	v_lshlrev_b64 v[126:127], 12, v[94:95]
	v_mad_u64_u32 v[130:131], s[46:47], v94, s85, v[6:7]
	v_or_b32_e32 v94, s57, v2
	global_load_dword v131, v[116:117], off
	global_load_dword v151, v[120:121], off
	v_lshl_add_u64 v[116:117], v[14:15], 0, v[126:127]
	v_lshlrev_b64 v[120:121], 12, v[94:95]
	v_mad_u64_u32 v[126:127], s[46:47], v94, s85, v[6:7]
	v_or_b32_e32 v94, s59, v2
	v_mad_u64_u32 v[134:135], s[46:47], v94, s85, v[6:7]
	v_lshl_add_u64 v[120:121], v[14:15], 0, v[120:121]
	global_load_dword v127, v[116:117], off
	global_load_dword v135, v[120:121], off
	v_lshlrev_b64 v[132:133], 12, v[94:95]
	v_or_b32_e32 v94, s60, v2
	v_lshl_add_u64 v[116:117], v[14:15], 0, v[132:133]
	v_lshlrev_b64 v[120:121], 12, v[94:95]
	global_load_dword v132, v[116:117], off
	v_lshl_add_u64 v[116:117], v[14:15], 0, v[120:121]
	global_load_dword v120, v[116:117], off
	s_add_i32 s43, s43, 16
	s_add_i32 s3, s3, 16
	s_add_i32 s44, s44, -16
	s_cmp_lg_u32 s44, 0
	v_mad_u64_u32 v[16:17], s[46:47], v16, s85, v[6:7]
	v_mad_u64_u32 v[22:23], s[46:47], v22, s85, v[6:7]
	v_mad_u64_u32 v[24:25], s[46:47], v24, s85, v[6:7]
	v_mad_u64_u32 v[26:27], s[46:47], v26, s85, v[6:7]
	v_mad_u64_u32 v[28:29], s[46:47], v28, s85, v[6:7]
	v_mad_u64_u32 v[30:31], s[46:47], v30, s85, v[6:7]
	v_mad_u64_u32 v[32:33], s[46:47], v32, s85, v[6:7]
	v_mad_u64_u32 v[34:35], s[46:47], v34, s85, v[6:7]
	v_mad_u64_u32 v[36:37], s[46:47], v0, s85, v[6:7]
	s_waitcnt vmcnt(31)
	ds_write_b32 v42, v5
	s_waitcnt vmcnt(30)
	ds_write_b32 v16, v21
	s_waitcnt vmcnt(29)
	ds_write_b32 v48, v39
	s_waitcnt vmcnt(28)
	ds_write_b32 v22, v43
	s_waitcnt vmcnt(21)
	ds_write_b32 v64, v51
	ds_write_b32 v24, v45
	s_waitcnt vmcnt(20)
	ds_write_b32 v44, v59
	ds_write_b32 v26, v49
	s_waitcnt vmcnt(19)
	ds_write_b32 v50, v47
	ds_write_b32 v28, v62
	s_waitcnt vmcnt(18)
	ds_write_b32 v46, v55
	ds_write_b32 v30, v56
	s_waitcnt vmcnt(17)
	ds_write_b32 v54, v52
	ds_write_b32 v32, v57
	s_waitcnt vmcnt(16)
	ds_write_b32 v36, v40
	ds_write_b32 v34, v58
	v_mad_u64_u32 v[98:99], s[46:47], v98, s85, v[6:7]
	v_mad_u64_u32 v[102:103], s[46:47], v102, s85, v[6:7]
	v_mad_u64_u32 v[104:105], s[46:47], v104, s85, v[6:7]
	v_mad_u64_u32 v[106:107], s[46:47], v106, s85, v[6:7]
	v_mad_u64_u32 v[108:109], s[46:47], v108, s85, v[6:7]
	v_mad_u64_u32 v[110:111], s[46:47], v110, s85, v[6:7]
	v_mad_u64_u32 v[112:113], s[46:47], v112, s85, v[6:7]
	v_mad_u64_u32 v[114:115], s[46:47], v114, s85, v[6:7]
	v_mad_u64_u32 v[116:117], s[46:47], v94, s85, v[6:7]
	s_waitcnt vmcnt(15)
	ds_write_b32 v122, v97
	s_waitcnt vmcnt(14)
	ds_write_b32 v98, v101
	s_waitcnt vmcnt(13)
	ds_write_b32 v128, v119
	s_waitcnt vmcnt(12)
	ds_write_b32 v102, v123
	s_waitcnt vmcnt(5)
	ds_write_b32 v156, v131
	ds_write_b32 v104, v125
	s_waitcnt vmcnt(4)
	ds_write_b32 v124, v151
	ds_write_b32 v106, v129
	s_waitcnt vmcnt(3)
	ds_write_b32 v130, v127
	ds_write_b32 v108, v154
	s_waitcnt vmcnt(2)
	ds_write_b32 v126, v135
	ds_write_b32 v110, v136
	s_waitcnt vmcnt(1)
	ds_write_b32 v134, v132
	ds_write_b32 v112, v137
	s_waitcnt vmcnt(0)
	ds_write_b32 v116, v120
	ds_write_b32 v114, v150
	s_waitcnt lgkmcnt(0)
	ds_read2_b32 v[14:15], v9 offset1:33
	s_waitcnt lgkmcnt(0)
	v_cvt_pk_bf16_f32 v14, v14, v15
	ds_read2_b32 v[16:17], v9 offset0:66 offset1:99
	s_lshl_b64 s[44:45], s[0:1], 17
	v_or_b32_e32 v0, s2, v7
	s_waitcnt lgkmcnt(0)
	v_cvt_pk_bf16_f32 v15, v16, v17
	ds_read2_b32 v[16:17], v9 offset0:132 offset1:165
	v_lshl_add_u64 v[24:25], v[10:11], 0, s[44:45]
	v_lshlrev_b32_e32 v0, 7, v0
	s_waitcnt lgkmcnt(0)
	v_cvt_pk_bf16_f32 v16, v16, v17
	ds_read2_b32 v[22:23], v9 offset0:198 offset1:231
	s_waitcnt lgkmcnt(0)
	v_cvt_pk_bf16_f32 v17, v22, v23
	v_lshl_add_u64 v[26:27], v[24:25], 0, v[0:1]
	ds_read2_b32 v[22:23], v9 offset0:8 offset1:41
	global_store_dwordx4 v[26:27], v[14:17], off sc1
	v_or_b32_e32 v0, s2, v18
	v_lshlrev_b32_e32 v0, 7, v0
	s_waitcnt lgkmcnt(0)
	v_cvt_pk_bf16_f32 v14, v22, v23
	ds_read2_b32 v[16:17], v9 offset0:74 offset1:107
	s_waitcnt lgkmcnt(0)
	v_cvt_pk_bf16_f32 v15, v16, v17
	ds_read2_b32 v[16:17], v9 offset0:140 offset1:173
	s_waitcnt lgkmcnt(0)
	v_cvt_pk_bf16_f32 v16, v16, v17
	ds_read2_b32 v[22:23], v9 offset0:206 offset1:239
	s_waitcnt lgkmcnt(0)
	v_cvt_pk_bf16_f32 v17, v22, v23
	v_lshl_add_u64 v[26:27], v[24:25], 0, v[0:1]
	ds_read2_b32 v[22:23], v9 offset0:16 offset1:49
	global_store_dwordx4 v[26:27], v[14:17], off sc1
	v_or_b32_e32 v0, s2, v19
	v_lshlrev_b32_e32 v0, 7, v0
	s_waitcnt lgkmcnt(0)
	v_cvt_pk_bf16_f32 v14, v22, v23
	ds_read2_b32 v[16:17], v9 offset0:82 offset1:115
	s_waitcnt lgkmcnt(0)
	v_cvt_pk_bf16_f32 v15, v16, v17
	ds_read2_b32 v[16:17], v9 offset0:148 offset1:181
	s_waitcnt lgkmcnt(0)
	v_cvt_pk_bf16_f32 v16, v16, v17
	ds_read2_b32 v[22:23], v9 offset0:214 offset1:247
	s_waitcnt lgkmcnt(0)
	v_cvt_pk_bf16_f32 v17, v22, v23
	v_lshl_add_u64 v[26:27], v[24:25], 0, v[0:1]
	ds_read2_b32 v[22:23], v9 offset0:24 offset1:57
	global_store_dwordx4 v[26:27], v[14:17], off sc1
	v_or_b32_e32 v0, s2, v20
	v_lshlrev_b32_e32 v0, 7, v0
	s_waitcnt lgkmcnt(0)
	v_cvt_pk_bf16_f32 v14, v22, v23
	ds_read2_b32 v[16:17], v9 offset0:90 offset1:123
	s_waitcnt lgkmcnt(0)
	v_cvt_pk_bf16_f32 v15, v16, v17
	ds_read2_b32 v[16:17], v9 offset0:156 offset1:189
	s_waitcnt lgkmcnt(0)
	v_cvt_pk_bf16_f32 v16, v16, v17
	ds_read2_b32 v[22:23], v9 offset0:222 offset1:255
	s_waitcnt lgkmcnt(0)
	v_cvt_pk_bf16_f32 v17, v22, v23
	v_lshl_add_u64 v[22:23], v[24:25], 0, v[0:1]
	global_store_dwordx4 v[22:23], v[14:17], off sc1
	s_waitcnt lgkmcnt(0)
	v_readlane_b32 s70, v253, 44
	s_mov_b64 s[2:3], 0
	v_readlane_b32 s71, v253, 45
	s_mov_b32 s48, 0x3a000000

;     ...
; #pragma unroll 8
;     for (int i = 0; i < 32; ++i) { const int kk = 2 * i + (lane >> 5); scr[kk * 33 + (lane & 31)] = W[(size_t)(k0 + kk) * N + n0 + (lane & 31)]; }
; __device__ __forceinline__ void phase_convert(const Args& a, LAS unsigned char* lds) {
;     ...
;         transpose_item(a.in[I_A2] + (size_t)l * 64 * DA, 64, DA, (bf16*)(ws + WS_A2T) + (size_t)l * DA * 64, 1 << 30, scr, r, lane);
.LBB0_479:
	s_lshl_b32 s41, s3, 1
	s_lshl_b32 s43, s38, 1
	v_or_b32_e32 v0, s43, v2
	s_add_i32 s46, s41, 4
	s_add_i32 s47, s43, 4
	v_mov_b32_e32 v23, v1
	s_add_i32 s48, s41, 8
	s_add_i32 s49, s43, 8
	s_add_i32 s54, s41, 20
	s_add_i32 s56, s41, 24
	v_lshlrev_b64 v[40:41], 12, v[0:1]
	v_mad_u64_u32 v[42:43], s[44:45], v0, s85, v[6:7]
	v_or_b32_e32 v22, s46, v3
	v_or_b32_e32 v0, s47, v2
	v_mov_b32_e32 v17, v1
	v_mov_b32_e32 v25, v1
	v_mov_b32_e32 v31, v1
	v_mov_b32_e32 v33, v1
	v_or_b32_e32 v16, s41, v3
	s_add_i32 s50, s41, 12
	s_add_i32 s51, s43, 12
	s_add_i32 s52, s41, 16
	s_add_i32 s41, s41, 28
	v_or_b32_e32 v24, s48, v3
	v_or_b32_e32 v30, s54, v3
	v_or_b32_e32 v32, s56, v3
	v_lshlrev_b64 v[44:45], 12, v[22:23]
	v_lshlrev_b64 v[46:47], 12, v[0:1]
	v_mad_u64_u32 v[48:49], s[44:45], v0, s85, v[6:7]
	v_or_b32_e32 v0, s49, v2
	v_mov_b32_e32 v27, v1
	v_mov_b32_e32 v29, v1
	v_mov_b32_e32 v35, v1
	s_add_i32 s53, s43, 16
	v_lshlrev_b64 v[36:37], 12, v[16:17]
	v_or_b32_e32 v26, s50, v3
	v_or_b32_e32 v28, s52, v3
	v_or_b32_e32 v34, s41, v3
	v_lshl_add_u64 v[40:41], v[14:15], 0, v[40:41]
	v_lshlrev_b64 v[50:51], 12, v[24:25]
	v_lshlrev_b64 v[56:57], 12, v[30:31]
	v_lshlrev_b64 v[58:59], 12, v[32:33]
	v_lshl_add_u64 v[44:45], v[14:15], 0, v[44:45]
	v_lshlrev_b64 v[62:63], 12, v[0:1]
	v_mad_u64_u32 v[64:65], s[44:45], v0, s85, v[6:7]
	v_or_b32_e32 v0, s51, v2
	s_add_i32 s55, s43, 20
	v_lshl_add_u64 v[36:37], v[14:15], 0, v[36:37]
	v_lshlrev_b64 v[52:53], 12, v[26:27]
	v_lshlrev_b64 v[54:55], 12, v[28:29]
	v_lshlrev_b64 v[60:61], 12, v[34:35]
	v_lshl_add_u64 v[46:47], v[14:15], 0, v[46:47]
	v_lshl_add_u64 v[50:51], v[14:15], 0, v[50:51]
	v_lshl_add_u64 v[56:57], v[14:15], 0, v[56:57]
	v_lshl_add_u64 v[58:59], v[14:15], 0, v[58:59]
	global_load_dword v5, v[40:41], off
	global_load_dword v21, v[36:37], off
	global_load_dword v39, v[46:47], off
	global_load_dword v43, v[44:45], off
	v_lshlrev_b64 v[40:41], 12, v[0:1]
	v_mad_u64_u32 v[44:45], s[44:45], v0, s85, v[6:7]
	v_or_b32_e32 v0, s53, v2
	s_add_i32 s57, s43, 24
	v_lshl_add_u64 v[52:53], v[14:15], 0, v[52:53]
	v_lshl_add_u64 v[54:55], v[14:15], 0, v[54:55]
	v_lshl_add_u64 v[60:61], v[14:15], 0, v[60:61]
	v_lshl_add_u64 v[36:37], v[14:15], 0, v[62:63]
	global_load_dword v45, v[50:51], off
	global_load_dword v49, v[52:53], off
	global_load_dword v62, v[54:55], off
	s_nop 0
	global_load_dword v56, v[56:57], off
	s_nop 0
	global_load_dword v57, v[58:59], off
	s_nop 0
	global_load_dword v58, v[60:61], off
	v_lshl_add_u64 v[40:41], v[14:15], 0, v[40:41]
	v_lshlrev_b64 v[46:47], 12, v[0:1]
	v_mad_u64_u32 v[50:51], s[44:45], v0, s85, v[6:7]
	v_or_b32_e32 v0, s55, v2
	global_load_dword v51, v[36:37], off
	global_load_dword v59, v[40:41], off
	v_lshl_add_u64 v[36:37], v[14:15], 0, v[46:47]
	v_lshlrev_b64 v[40:41], 12, v[0:1]
	v_mad_u64_u32 v[46:47], s[44:45], v0, s85, v[6:7]
	v_or_b32_e32 v0, s57, v2
	v_mad_u64_u32 v[54:55], s[44:45], v0, s85, v[6:7]
	v_lshl_add_u64 v[40:41], v[14:15], 0, v[40:41]
	global_load_dword v47, v[36:37], off
	global_load_dword v55, v[40:41], off
	s_add_i32 s43, s43, 28
	v_lshlrev_b64 v[52:53], 12, v[0:1]
	v_or_b32_e32 v0, s43, v2
	v_lshl_add_u64 v[36:37], v[14:15], 0, v[52:53]
	v_lshlrev_b64 v[40:41], 12, v[0:1]
	global_load_dword v52, v[36:37], off
	v_lshl_add_u64 v[36:37], v[14:15], 0, v[40:41]
	global_load_dword v40, v[36:37], off
	s_add_i32 s38, s38, 16
	s_add_i32 s3, s3, 16
	s_add_i32 s39, s39, -16
	s_cmp_lg_u32 s39, 0
	v_mov_b32_e32 v95, 0
	s_lshl_b32 s41, s3, 1
	s_lshl_b32 s43, s38, 1
	v_or_b32_e32 v94, s43, v2
	s_add_i32 s46, s41, 4
	s_add_i32 s47, s43, 4
	v_mov_b32_e32 v103, v95
	s_add_i32 s48, s41, 8
	s_add_i32 s49, s43, 8
	s_add_i32 s54, s41, 20
	s_add_i32 s56, s41, 24
	v_lshlrev_b64 v[120:121], 12, v[94:95]
	v_mad_u64_u32 v[122:123], s[44:45], v94, s85, v[6:7]
	v_or_b32_e32 v102, s46, v3
	v_or_b32_e32 v94, s47, v2
	v_mov_b32_e32 v99, v95
	v_mov_b32_e32 v105, v95
	v_mov_b32_e32 v111, v95
	v_mov_b32_e32 v113, v95
	v_or_b32_e32 v98, s41, v3
	s_add_i32 s50, s41, 12
	s_add_i32 s51, s43, 12
	s_add_i32 s52, s41, 16
	s_add_i32 s41, s41, 28
	v_or_b32_e32 v104, s48, v3
	v_or_b32_e32 v110, s54, v3
	v_or_b32_e32 v112, s56, v3
	v_lshlrev_b64 v[124:125], 12, v[102:103]
	v_lshlrev_b64 v[126:127], 12, v[94:95]
	v_mad_u64_u32 v[128:129], s[44:45], v94, s85, v[6:7]
	v_or_b32_e32 v94, s49, v2
	v_mov_b32_e32 v107, v95
	v_mov_b32_e32 v109, v95
	v_mov_b32_e32 v115, v95
	s_add_i32 s53, s43, 16
	v_lshlrev_b64 v[116:117], 12, v[98:99]
	v_or_b32_e32 v106, s50, v3
	v_or_b32_e32 v108, s52, v3
	v_or_b32_e32 v114, s41, v3
	v_lshl_add_u64 v[120:121], v[14:15], 0, v[120:121]
	v_lshlrev_b64 v[130:131], 12, v[104:105]
	v_lshlrev_b64 v[136:137], 12, v[110:111]
	v_lshlrev_b64 v[150:151], 12, v[112:113]
	v_lshl_add_u64 v[124:125], v[14:15], 0, v[124:125]
	v_lshlrev_b64 v[154:155], 12, v[94:95]
	v_mad_u64_u32 v[156:157], s[44:45], v94, s85, v[6:7]
	v_or_b32_e32 v94, s51, v2
	s_add_i32 s55, s43, 20
	v_lshl_add_u64 v[116:117], v[14:15], 0, v[116:117]
	v_lshlrev_b64 v[132:133], 12, v[106:107]
	v_lshlrev_b64 v[134:135], 12, v[108:109]
	v_lshlrev_b64 v[152:153], 12, v[114:115]
	v_lshl_add_u64 v[126:127], v[14:15], 0, v[126:127]
	v_lshl_add_u64 v[130:131], v[14:15], 0, v[130:131]
	v_lshl_add_u64 v[136:137], v[14:15], 0, v[136:137]
	v_lshl_add_u64 v[150:151], v[14:15], 0, v[150:151]
	global_load_dword v97, v[120:121], off
	global_load_dword v101, v[116:117], off
	global_load_dword v119, v[126:127], off
	global_load_dword v123, v[124:125], off
	v_lshlrev_b64 v[120:121], 12, v[94:95]
	v_mad_u64_u32 v[124:125], s[44:45], v94, s85, v[6:7]
	v_or_b32_e32 v94, s53, v2
	s_add_i32 s57, s43, 24
	v_lshl_add_u64 v[132:133], v[14:15], 0, v[132:133]
; __device__ __forceinline__ unsigned cvt_pk_bf16(float lo, float hi) { unsigned r; asm volatile("v_cvt_pk_bf16_f32 %0, %1, %2" : "=v"(r) : "v"(lo), "v"(hi)); return r; }
; #define LAS __attribute__((address_space(3)))
; #define LDS_WAIT() asm volatile("s_waitcnt lgkmcnt(0)" ::: "memory")
;     ...
;     for (int i = 0; i < 32; ++i) { const int kk = 2 * i + (lane >> 5); scr[kk * 33 + (lane & 31)] = W[(size_t)(k0 + kk) * N + n0 + (lane & 31)]; }
;     LDS_WAIT(); asm volatile("" ::: "memory");
;     const int c = lane & 7;
; #pragma unroll
;     for (int j = 0; j < 4; ++j) { const int n = (lane >> 3) + 8 * j; const LAS float* s = scr + (8 * c) * 33 + n;
;         u32x4 o; o.x = cvt_pk_bf16(s[0 * 33], s[1 * 33]); o.y = cvt_pk_bf16(s[2 * 33], s[3 * 33]); o.z = cvt_pk_bf16(s[4 * 33], s[5 * 33]); o.w = cvt_pk_bf16(s[6 * 33], s[7 * 33]);
;         *(u32x4*)(WT + (size_t)(dn0 + n) * ldo + koff + k0 + 8 * c) = o; }
;     LDS_WAIT(); asm volatile("" ::: "memory");
	v_lshl_add_u64 v[134:135], v[14:15], 0, v[134:135]
	v_lshl_add_u64 v[152:153], v[14:15], 0, v[152:153]
	v_lshl_add_u64 v[116:117], v[14:15], 0, v[154:155]
	global_load_dword v125, v[130:131], off
	global_load_dword v129, v[132:133], off
	global_load_dword v154, v[134:135], off
	s_nop 0
	global_load_dword v136, v[136:137], off
	s_nop 0
	global_load_dword v137, v[150:151], off
	s_nop 0
	global_load_dword v150, v[152:153], off
	v_lshl_add_u64 v[120:121], v[14:15], 0, v[120:121]
	v_lshlrev_b64 v[126:127], 12, v[94:95]
	v_mad_u64_u32 v[130:131], s[44:45], v94, s85, v[6:7]
	v_or_b32_e32 v94, s55, v2
	global_load_dword v131, v[116:117], off
	global_load_dword v151, v[120:121], off
	v_lshl_add_u64 v[116:117], v[14:15], 0, v[126:127]
	v_lshlrev_b64 v[120:121], 12, v[94:95]
	v_mad_u64_u32 v[126:127], s[44:45], v94, s85, v[6:7]
	v_or_b32_e32 v94, s57, v2
	v_mad_u64_u32 v[134:135], s[44:45], v94, s85, v[6:7]
	v_lshl_add_u64 v[120:121], v[14:15], 0, v[120:121]
	global_load_dword v127, v[116:117], off
	global_load_dword v135, v[120:121], off
	s_add_i32 s43, s43, 28
	v_lshlrev_b64 v[132:133], 12, v[94:95]
	v_or_b32_e32 v94, s43, v2
	v_lshl_add_u64 v[116:117], v[14:15], 0, v[132:133]
	v_lshlrev_b64 v[120:121], 12, v[94:95]
	global_load_dword v132, v[116:117], off
	v_lshl_add_u64 v[116:117], v[14:15], 0, v[120:121]
	global_load_dword v120, v[116:117], off
	s_add_i32 s38, s38, 16
	s_add_i32 s3, s3, 16
	s_add_i32 s39, s39, -16
	s_cmp_lg_u32 s39, 0
	v_mad_u64_u32 v[16:17], s[44:45], v16, s85, v[6:7]
	v_mad_u64_u32 v[22:23], s[44:45], v22, s85, v[6:7]
	v_mad_u64_u32 v[24:25], s[44:45], v24, s85, v[6:7]
	v_mad_u64_u32 v[26:27], s[44:45], v26, s85, v[6:7]
	v_mad_u64_u32 v[28:29], s[44:45], v28, s85, v[6:7]
	v_mad_u64_u32 v[30:31], s[44:45], v30, s85, v[6:7]
	v_mad_u64_u32 v[32:33], s[44:45], v32, s85, v[6:7]
	v_mad_u64_u32 v[34:35], s[44:45], v34, s85, v[6:7]
	v_mad_u64_u32 v[36:37], s[44:45], v0, s85, v[6:7]
	s_waitcnt vmcnt(31)
	ds_write_b32 v42, v5
	s_waitcnt vmcnt(30)
	ds_write_b32 v16, v21
	s_waitcnt vmcnt(29)
	ds_write_b32 v48, v39
	s_waitcnt vmcnt(28)
	ds_write_b32 v22, v43
	s_waitcnt vmcnt(21)
	ds_write_b32 v64, v51
	ds_write_b32 v24, v45
	s_waitcnt vmcnt(20)
	ds_write_b32 v44, v59
	ds_write_b32 v26, v49
	s_waitcnt vmcnt(19)
	ds_write_b32 v50, v47
	ds_write_b32 v28, v62
	s_waitcnt vmcnt(18)
	ds_write_b32 v46, v55
	ds_write_b32 v30, v56
	s_waitcnt vmcnt(17)
	ds_write_b32 v54, v52
	ds_write_b32 v32, v57
	s_waitcnt vmcnt(16)
	ds_write_b32 v36, v40
	ds_write_b32 v34, v58
	v_mad_u64_u32 v[98:99], s[44:45], v98, s85, v[6:7]
	v_mad_u64_u32 v[102:103], s[44:45], v102, s85, v[6:7]
	v_mad_u64_u32 v[104:105], s[44:45], v104, s85, v[6:7]
	v_mad_u64_u32 v[106:107], s[44:45], v106, s85, v[6:7]
	v_mad_u64_u32 v[108:109], s[44:45], v108, s85, v[6:7]
	v_mad_u64_u32 v[110:111], s[44:45], v110, s85, v[6:7]
	v_mad_u64_u32 v[112:113], s[44:45], v112, s85, v[6:7]
	v_mad_u64_u32 v[114:115], s[44:45], v114, s85, v[6:7]
	v_mad_u64_u32 v[116:117], s[44:45], v94, s85, v[6:7]
	s_waitcnt vmcnt(15)
	ds_write_b32 v122, v97
	s_waitcnt vmcnt(14)
	ds_write_b32 v98, v101
	s_waitcnt vmcnt(13)
	ds_write_b32 v128, v119
	s_waitcnt vmcnt(12)
	ds_write_b32 v102, v123
	s_waitcnt vmcnt(5)
	ds_write_b32 v156, v131
	ds_write_b32 v104, v125
	s_waitcnt vmcnt(4)
	ds_write_b32 v124, v151
	ds_write_b32 v106, v129
	s_waitcnt vmcnt(3)
	ds_write_b32 v130, v127
	ds_write_b32 v108, v154
	s_waitcnt vmcnt(2)
	ds_write_b32 v126, v135
	ds_write_b32 v110, v136
	s_waitcnt vmcnt(1)
	ds_write_b32 v134, v132
	ds_write_b32 v112, v137
	s_waitcnt vmcnt(0)
	ds_write_b32 v116, v120
	ds_write_b32 v114, v150
	s_waitcnt lgkmcnt(0)
	ds_read2_b32 v[14:15], v9 offset1:33
	s_waitcnt lgkmcnt(0)
	v_cvt_pk_bf16_f32 v14, v14, v15
	ds_read2_b32 v[16:17], v9 offset0:66 offset1:99
	s_lshl_b64 s[38:39], s[0:1], 17
	v_or_b32_e32 v0, s2, v7
	s_waitcnt lgkmcnt(0)
	v_cvt_pk_bf16_f32 v15, v16, v17
	ds_read2_b32 v[16:17], v9 offset0:132 offset1:165
	v_lshl_add_u64 v[24:25], v[12:13], 0, s[38:39]
	v_lshlrev_b32_e32 v0, 7, v0
	s_waitcnt lgkmcnt(0)
	v_cvt_pk_bf16_f32 v16, v16, v17
	ds_read2_b32 v[22:23], v9 offset0:198 offset1:231
	s_waitcnt lgkmcnt(0)
	v_cvt_pk_bf16_f32 v17, v22, v23
	v_lshl_add_u64 v[26:27], v[24:25], 0, v[0:1]
	ds_read2_b32 v[22:23], v9 offset0:8 offset1:41
	global_store_dwordx4 v[26:27], v[14:17], off sc1
	v_or_b32_e32 v0, s2, v18
	v_lshlrev_b32_e32 v0, 7, v0
	s_waitcnt lgkmcnt(0)
	v_cvt_pk_bf16_f32 v14, v22, v23
	ds_read2_b32 v[16:17], v9 offset0:74 offset1:107
	s_waitcnt lgkmcnt(0)
	v_cvt_pk_bf16_f32 v15, v16, v17
	ds_read2_b32 v[16:17], v9 offset0:140 offset1:173
	s_waitcnt lgkmcnt(0)
	v_cvt_pk_bf16_f32 v16, v16, v17
	ds_read2_b32 v[22:23], v9 offset0:206 offset1:239
	s_waitcnt lgkmcnt(0)
	v_cvt_pk_bf16_f32 v17, v22, v23
	v_lshl_add_u64 v[26:27], v[24:25], 0, v[0:1]
	ds_read2_b32 v[22:23], v9 offset0:16 offset1:49
	global_store_dwordx4 v[26:27], v[14:17], off sc1
	v_or_b32_e32 v0, s2, v19
	v_lshlrev_b32_e32 v0, 7, v0
	s_waitcnt lgkmcnt(0)
	v_cvt_pk_bf16_f32 v14, v22, v23
	ds_read2_b32 v[16:17], v9 offset0:82 offset1:115
	s_waitcnt lgkmcnt(0)
	v_cvt_pk_bf16_f32 v15, v16, v17
	ds_read2_b32 v[16:17], v9 offset0:148 offset1:181
	s_waitcnt lgkmcnt(0)
	v_cvt_pk_bf16_f32 v16, v16, v17
	ds_read2_b32 v[22:23], v9 offset0:214 offset1:247
	s_waitcnt lgkmcnt(0)
	v_cvt_pk_bf16_f32 v17, v22, v23
	v_lshl_add_u64 v[26:27], v[24:25], 0, v[0:1]
	ds_read2_b32 v[22:23], v9 offset0:24 offset1:57
	global_store_dwordx4 v[26:27], v[14:17], off sc1
	v_or_b32_e32 v0, s2, v20
	v_lshlrev_b32_e32 v0, 7, v0
	s_waitcnt lgkmcnt(0)
	v_cvt_pk_bf16_f32 v14, v22, v23
	ds_read2_b32 v[16:17], v9 offset0:90 offset1:123
	s_waitcnt lgkmcnt(0)
	v_cvt_pk_bf16_f32 v15, v16, v17
	ds_read2_b32 v[16:17], v9 offset0:156 offset1:189
	s_waitcnt lgkmcnt(0)
	v_cvt_pk_bf16_f32 v16, v16, v17
	ds_read2_b32 v[22:23], v9 offset0:222 offset1:255
	s_waitcnt lgkmcnt(0)
	v_cvt_pk_bf16_f32 v17, v22, v23
	v_lshl_add_u64 v[22:23], v[24:25], 0, v[0:1]
	global_store_dwordx4 v[22:23], v[14:17], off sc1
	s_waitcnt lgkmcnt(0)
	s_mov_b32 s48, 0x3a000000

;     ...
; #pragma unroll 8
;     for (int i = 0; i < 32; ++i) { const int kk = 2 * i + (lane >> 5); scr[kk * 33 + (lane & 31)] = W[(size_t)(k0 + kk) * N + n0 + (lane & 31)]; }
; __device__ __forceinline__ void phase_convert(const Args& a, LAS unsigned char* lds) {
;     ...
;         if (r < I_P) { transpose_item(a.in[I_PA] + (size_t)l * DA * D, DA, D, (bf16*)(ws + WS_WPAB) + (size_t)l * D * D, 1 << 30, scr, r, lane, D, 0); continue; } r -= I_P;
.LBB0_484:
	s_lshl_b32 s46, s43, 1
	s_lshl_b32 s45, s41, 1
	v_or_b32_e32 v0, s46, v16
	s_add_i32 s49, s46, 4
	s_add_i32 s48, s45, 4
	s_add_i32 s50, s45, 8
	s_add_i32 s51, s46, 8
	v_lshlrev_b64 v[40:41], 13, v[0:1]
	v_or_b32_e32 v0, s49, v16
	v_mov_b32_e32 v23, v1
	v_mov_b32_e32 v25, v1
	v_mov_b32_e32 v27, v1
	v_or_b32_e32 v22, s45, v5
	s_add_i32 s52, s45, 12
	s_add_i32 s53, s46, 12
	s_add_i32 s54, s45, 16
	s_add_i32 s56, s45, 20
	s_add_i32 s58, s45, 24
	s_add_i32 s60, s45, 28
	v_or_b32_e32 v24, s48, v5
	v_or_b32_e32 v26, s50, v5
	v_lshlrev_b64 v[42:43], 13, v[0:1]
	v_or_b32_e32 v0, s51, v16
	v_mov_b32_e32 v29, v1
	v_mov_b32_e32 v31, v1
	v_mov_b32_e32 v33, v1
	v_mov_b32_e32 v35, v1
	v_mov_b32_e32 v37, v1
	s_add_i32 s55, s46, 16
	v_lshlrev_b64 v[22:23], 13, v[22:23]
	v_or_b32_e32 v28, s52, v5
	v_or_b32_e32 v30, s54, v5
	v_or_b32_e32 v32, s56, v5
	v_or_b32_e32 v34, s58, v5
	v_or_b32_e32 v36, s60, v5
	v_lshl_add_u64 v[40:41], v[14:15], 0, v[40:41]
	v_lshlrev_b64 v[24:25], 13, v[24:25]
	v_lshlrev_b64 v[26:27], 13, v[26:27]
	v_lshlrev_b64 v[44:45], 13, v[0:1]
	v_or_b32_e32 v0, s53, v16
	s_add_i32 s57, s46, 20
	v_lshl_add_u64 v[22:23], v[14:15], 0, v[22:23]
	v_lshlrev_b64 v[28:29], 13, v[28:29]
	v_lshlrev_b64 v[30:31], 13, v[30:31]
	v_lshlrev_b64 v[32:33], 13, v[32:33]
	v_lshlrev_b64 v[34:35], 13, v[34:35]
	v_lshlrev_b64 v[36:37], 13, v[36:37]
	v_lshl_add_u64 v[42:43], v[14:15], 0, v[42:43]
	v_lshl_add_u64 v[24:25], v[14:15], 0, v[24:25]
	v_lshl_add_u64 v[26:27], v[14:15], 0, v[26:27]
	global_load_dword v17, v[40:41], off
	global_load_dword v21, v[22:23], off
	v_lshlrev_b64 v[40:41], 13, v[0:1]
	v_or_b32_e32 v0, s55, v16
	s_add_i32 s59, s46, 24
	v_lshl_add_u64 v[28:29], v[14:15], 0, v[28:29]
	v_lshl_add_u64 v[30:31], v[14:15], 0, v[30:31]
	v_lshl_add_u64 v[32:33], v[14:15], 0, v[32:33]
	v_lshl_add_u64 v[34:35], v[14:15], 0, v[34:35]
	v_lshl_add_u64 v[36:37], v[14:15], 0, v[36:37]
	global_load_dword v39, v[42:43], off
	global_load_dword v56, v[24:25], off
	global_load_dword v57, v[26:27], off
	global_load_dword v58, v[28:29], off
	global_load_dword v59, v[30:31], off
	global_load_dword v60, v[32:33], off
	global_load_dword v61, v[34:35], off
	global_load_dword v62, v[36:37], off
	v_lshl_add_u64 v[24:25], v[14:15], 0, v[40:41]
	v_lshlrev_b64 v[26:27], 13, v[0:1]
	v_or_b32_e32 v0, s57, v16
	s_add_i32 s61, s46, 28
	v_lshl_add_u64 v[22:23], v[14:15], 0, v[44:45]
	global_load_dword v63, v[24:25], off
	global_load_dword v64, v[22:23], off
	v_lshlrev_b64 v[24:25], 13, v[0:1]
	v_or_b32_e32 v0, s59, v16
	v_lshl_add_u64 v[22:23], v[14:15], 0, v[26:27]
	v_lshlrev_b64 v[26:27], 13, v[0:1]
	v_or_b32_e32 v0, s61, v16
	v_lshlrev_b64 v[28:29], 13, v[0:1]
	v_lshl_add_u64 v[28:29], v[14:15], 0, v[28:29]
	v_lshl_add_u64 v[24:25], v[14:15], 0, v[24:25]
	v_lshl_add_u64 v[26:27], v[14:15], 0, v[26:27]
	global_load_dword v0, v[28:29], off
	global_load_dword v65, v[26:27], off
	global_load_dword v66, v[24:25], off
	global_load_dword v67, v[22:23], off
	v_or_b32_e32 v214, s45, v3
	v_or_b32_e32 v215, s46, v2
	v_or_b32_e32 v216, s48, v3
	v_or_b32_e32 v217, s49, v2
	v_or_b32_e32 v218, s50, v3
	v_or_b32_e32 v219, s51, v2
	v_or_b32_e32 v220, s52, v3
	v_or_b32_e32 v221, s53, v2
	v_or_b32_e32 v222, s54, v3
	v_or_b32_e32 v223, s55, v2
	v_or_b32_e32 v224, s56, v3
	v_or_b32_e32 v225, s57, v2
	v_or_b32_e32 v226, s58, v3
	v_or_b32_e32 v227, s59, v2
	v_or_b32_e32 v228, s60, v3
	v_or_b32_e32 v229, s61, v2
	s_add_i32 s43, s43, 16
	s_add_i32 s41, s41, 16
	s_add_i32 s44, s44, -16
	s_cmp_lg_u32 s44, 0
	v_mov_b32_e32 v95, 0
	s_lshl_b32 s46, s43, 1
	s_lshl_b32 s45, s41, 1
	v_or_b32_e32 v94, s46, v16
	s_add_i32 s49, s46, 4
	s_add_i32 s48, s45, 4
	s_add_i32 s50, s45, 8
	s_add_i32 s51, s46, 8
	v_lshlrev_b64 v[118:119], 13, v[94:95]
	v_or_b32_e32 v94, s49, v16
	v_mov_b32_e32 v101, v95
	v_mov_b32_e32 v103, v95
	v_mov_b32_e32 v105, v95
	v_or_b32_e32 v100, s45, v5
	s_add_i32 s52, s45, 12
	s_add_i32 s53, s46, 12
	s_add_i32 s54, s45, 16
	s_add_i32 s56, s45, 20
	s_add_i32 s58, s45, 24
	s_add_i32 s60, s45, 28
	v_or_b32_e32 v102, s48, v5
	v_or_b32_e32 v104, s50, v5
	v_lshlrev_b64 v[120:121], 13, v[94:95]
	v_or_b32_e32 v94, s51, v16
	v_mov_b32_e32 v107, v95
	v_mov_b32_e32 v109, v95
	v_mov_b32_e32 v111, v95
	v_mov_b32_e32 v113, v95
	v_mov_b32_e32 v115, v95
	s_add_i32 s55, s46, 16
	v_lshlrev_b64 v[100:101], 13, v[100:101]
	v_or_b32_e32 v106, s52, v5
	v_or_b32_e32 v108, s54, v5
	v_or_b32_e32 v110, s56, v5
	v_or_b32_e32 v112, s58, v5
	v_or_b32_e32 v114, s60, v5
	v_lshl_add_u64 v[118:119], v[14:15], 0, v[118:119]
	v_lshlrev_b64 v[102:103], 13, v[102:103]
	v_lshlrev_b64 v[104:105], 13, v[104:105]
	v_lshlrev_b64 v[122:123], 13, v[94:95]
	v_or_b32_e32 v94, s53, v16
	s_add_i32 s57, s46, 20
	v_lshl_add_u64 v[100:101], v[14:15], 0, v[100:101]
	v_lshlrev_b64 v[106:107], 13, v[106:107]
	v_lshlrev_b64 v[108:109], 13, v[108:109]
	v_lshlrev_b64 v[110:111], 13, v[110:111]
	v_lshlrev_b64 v[112:113], 13, v[112:113]
	v_lshlrev_b64 v[114:115], 13, v[114:115]
	v_lshl_add_u64 v[120:121], v[14:15], 0, v[120:121]
	v_lshl_add_u64 v[102:103], v[14:15], 0, v[102:103]
	v_lshl_add_u64 v[104:105], v[14:15], 0, v[104:105]
	global_load_dword v97, v[118:119], off
	global_load_dword v99, v[100:101], off
	v_lshlrev_b64 v[118:119], 13, v[94:95]
	v_or_b32_e32 v94, s55, v16
	s_add_i32 s59, s46, 24
	v_lshl_add_u64 v[106:107], v[14:15], 0, v[106:107]
	v_lshl_add_u64 v[108:109], v[14:15], 0, v[108:109]
	v_lshl_add_u64 v[110:111], v[14:15], 0, v[110:111]
	v_lshl_add_u64 v[112:113], v[14:15], 0, v[112:113]
	v_lshl_add_u64 v[114:115], v[14:15], 0, v[114:115]
	global_load_dword v117, v[120:121], off
	global_load_dword v96, v[102:103], off
;     ...
;     for (int i = 0; i < 32; ++i) { const int kk = 2 * i + (lane >> 5); scr[kk * 33 + (lane & 31)] = W[(size_t)(k0 + kk) * N + n0 + (lane & 31)]; }
	global_load_dword v135, v[104:105], off
	global_load_dword v98, v[106:107], off
	global_load_dword v137, v[108:109], off
	global_load_dword v116, v[110:111], off
	global_load_dword v151, v[112:113], off
	global_load_dword v134, v[114:115], off
	v_lshl_add_u64 v[102:103], v[14:15], 0, v[118:119]
	v_lshlrev_b64 v[104:105], 13, v[94:95]
	v_or_b32_e32 v94, s57, v16
	s_add_i32 s61, s46, 28
	v_lshl_add_u64 v[100:101], v[14:15], 0, v[122:123]
	global_load_dword v153, v[102:103], off
	global_load_dword v136, v[100:101], off
	v_lshlrev_b64 v[102:103], 13, v[94:95]
	v_or_b32_e32 v94, s59, v16
	v_lshl_add_u64 v[100:101], v[14:15], 0, v[104:105]
	v_lshlrev_b64 v[104:105], 13, v[94:95]
	v_or_b32_e32 v94, s61, v16
	v_lshlrev_b64 v[106:107], 13, v[94:95]
	v_lshl_add_u64 v[106:107], v[14:15], 0, v[106:107]
	v_lshl_add_u64 v[102:103], v[14:15], 0, v[102:103]
	v_lshl_add_u64 v[104:105], v[14:15], 0, v[104:105]
	global_load_dword v94, v[106:107], off
	global_load_dword v155, v[104:105], off
	global_load_dword v138, v[102:103], off
	global_load_dword v157, v[100:101], off
	v_or_b32_e32 v150, s45, v3
	v_or_b32_e32 v159, s46, v2
	v_or_b32_e32 v152, s48, v3
	v_or_b32_e32 v161, s49, v2
	v_or_b32_e32 v154, s50, v3
	v_or_b32_e32 v163, s51, v2
	v_or_b32_e32 v156, s52, v3
	v_or_b32_e32 v165, s53, v2
	v_or_b32_e32 v158, s54, v3
	v_or_b32_e32 v167, s55, v2
	v_or_b32_e32 v160, s56, v3
	v_or_b32_e32 v169, s57, v2
	v_or_b32_e32 v162, s58, v3
	v_or_b32_e32 v183, s59, v2
	v_or_b32_e32 v164, s60, v3
	v_or_b32_e32 v185, s61, v2
	s_add_i32 s43, s43, 16
	s_add_i32 s41, s41, 16
	s_add_i32 s44, s44, -16
	s_cmp_lg_u32 s44, 0
	v_mad_u64_u32 v[22:23], s[46:47], v215, s85, v[6:7]
	v_mad_u64_u32 v[24:25], s[46:47], v214, s85, v[6:7]
	v_mad_u64_u32 v[26:27], s[46:47], v217, s85, v[6:7]
	v_mad_u64_u32 v[28:29], s[46:47], v216, s85, v[6:7]
	v_mad_u64_u32 v[30:31], s[46:47], v219, s85, v[6:7]
	v_mad_u64_u32 v[32:33], s[46:47], v218, s85, v[6:7]
	v_mad_u64_u32 v[34:35], s[46:47], v221, s85, v[6:7]
	v_mad_u64_u32 v[36:37], s[46:47], v220, s85, v[6:7]
	v_mad_u64_u32 v[40:41], s[46:47], v223, s85, v[6:7]
	v_mad_u64_u32 v[42:43], s[46:47], v222, s85, v[6:7]
	v_mad_u64_u32 v[44:45], s[46:47], v225, s85, v[6:7]
	v_mad_u64_u32 v[46:47], s[46:47], v224, s85, v[6:7]
	v_mad_u64_u32 v[48:49], s[46:47], v227, s85, v[6:7]
	v_mad_u64_u32 v[50:51], s[46:47], v226, s85, v[6:7]
	v_mad_u64_u32 v[52:53], s[46:47], v229, s85, v[6:7]
	v_mad_u64_u32 v[54:55], s[46:47], v228, s85, v[6:7]
	s_waitcnt vmcnt(31)
	ds_write_b32 v22, v17
	s_waitcnt vmcnt(30)
	ds_write_b32 v24, v21
	s_waitcnt vmcnt(29)
	ds_write_b32 v26, v39
	s_waitcnt vmcnt(28)
	ds_write_b32 v28, v56
	s_waitcnt vmcnt(20)
	ds_write_b32 v30, v64
	ds_write_b32 v32, v57
	ds_write_b32 v34, v63
	ds_write_b32 v36, v58
	s_waitcnt vmcnt(16)
	ds_write_b32 v40, v67
	ds_write_b32 v42, v59
	ds_write_b32 v44, v66
	ds_write_b32 v46, v60
	ds_write_b32 v48, v65
	ds_write_b32 v50, v61
	ds_write_b32 v52, v0
	ds_write_b32 v54, v62
	v_mad_u64_u32 v[100:101], s[46:47], v159, s85, v[6:7]
	v_mad_u64_u32 v[102:103], s[46:47], v150, s85, v[6:7]
	v_mad_u64_u32 v[104:105], s[46:47], v161, s85, v[6:7]
	v_mad_u64_u32 v[106:107], s[46:47], v152, s85, v[6:7]
	v_mad_u64_u32 v[108:109], s[46:47], v163, s85, v[6:7]
	v_mad_u64_u32 v[110:111], s[46:47], v154, s85, v[6:7]
	v_mad_u64_u32 v[112:113], s[46:47], v165, s85, v[6:7]
	v_mad_u64_u32 v[114:115], s[46:47], v156, s85, v[6:7]
	v_mad_u64_u32 v[118:119], s[46:47], v167, s85, v[6:7]
	v_mad_u64_u32 v[120:121], s[46:47], v158, s85, v[6:7]
	v_mad_u64_u32 v[122:123], s[46:47], v169, s85, v[6:7]
	v_mad_u64_u32 v[124:125], s[46:47], v160, s85, v[6:7]
	v_mad_u64_u32 v[126:127], s[46:47], v183, s85, v[6:7]
	v_mad_u64_u32 v[128:129], s[46:47], v162, s85, v[6:7]
	v_mad_u64_u32 v[130:131], s[46:47], v185, s85, v[6:7]
	v_mad_u64_u32 v[132:133], s[46:47], v164, s85, v[6:7]
	s_waitcnt vmcnt(15)
; __device__ __forceinline__ unsigned cvt_pk_bf16(float lo, float hi) { unsigned r; asm volatile("v_cvt_pk_bf16_f32 %0, %1, %2" : "=v"(r) : "v"(lo), "v"(hi)); return r; }
; #define LAS __attribute__((address_space(3)))
; #define LDS_WAIT() asm volatile("s_waitcnt lgkmcnt(0)" ::: "memory")
;     ...
;     for (int i = 0; i < 32; ++i) { const int kk = 2 * i + (lane >> 5); scr[kk * 33 + (lane & 31)] = W[(size_t)(k0 + kk) * N + n0 + (lane & 31)]; }
;     LDS_WAIT(); asm volatile("" ::: "memory");
;     const int c = lane & 7;
; #pragma unroll
;     for (int j = 0; j < 4; ++j) { const int n = (lane >> 3) + 8 * j; const LAS float* s = scr + (8 * c) * 33 + n;
;         u32x4 o; o.x = cvt_pk_bf16(s[0 * 33], s[1 * 33]); o.y = cvt_pk_bf16(s[2 * 33], s[3 * 33]); o.z = cvt_pk_bf16(s[4 * 33], s[5 * 33]); o.w = cvt_pk_bf16(s[6 * 33], s[7 * 33]);
;         *(u32x4*)(WT + (size_t)(dn0 + n) * ldo + koff + k0 + 8 * c) = o; }
;     LDS_WAIT(); asm volatile("" ::: "memory");
	ds_write_b32 v100, v97
	s_waitcnt vmcnt(14)
	ds_write_b32 v102, v99
	s_waitcnt vmcnt(13)
	ds_write_b32 v104, v117
	s_waitcnt vmcnt(12)
	ds_write_b32 v106, v96
	s_waitcnt vmcnt(4)
	ds_write_b32 v108, v136
	ds_write_b32 v110, v135
	ds_write_b32 v112, v153
	ds_write_b32 v114, v98
	s_waitcnt vmcnt(0)
	ds_write_b32 v118, v157
	ds_write_b32 v120, v137
	ds_write_b32 v122, v138
	ds_write_b32 v124, v116
	ds_write_b32 v126, v155
	ds_write_b32 v128, v151
	ds_write_b32 v130, v94
	ds_write_b32 v132, v134
	s_lshl_b64 s[38:39], s[38:39], 1
	v_readlane_b32 s41, v251, 18
	s_waitcnt lgkmcnt(0)
	s_add_u32 s38, s41, s38
	v_readlane_b32 s41, v251, 19
	s_addc_u32 s39, s41, s39
	s_lshl_b32 s3, s3, 1
	ds_read2_b32 v[14:15], v9 offset1:33
	s_add_u32 s38, s38, s3
	s_waitcnt lgkmcnt(0)
	v_cvt_pk_bf16_f32 v14, v14, v15
	ds_read2_b32 v[16:17], v9 offset0:66 offset1:99
	v_lshlrev_b32_e32 v0, 1, v8
	v_or_b32_e32 v5, s2, v7
	s_addc_u32 s39, s39, 0
	s_waitcnt lgkmcnt(0)
	v_cvt_pk_bf16_f32 v15, v16, v17
	ds_read2_b32 v[16:17], v9 offset0:132 offset1:165
	v_lshl_add_u64 v[24:25], s[38:39], 0, v[0:1]
	v_lshlrev_b32_e32 v0, 12, v5
	s_waitcnt lgkmcnt(0)
	v_cvt_pk_bf16_f32 v16, v16, v17
	ds_read2_b32 v[22:23], v9 offset0:198 offset1:231
	s_waitcnt lgkmcnt(0)
	v_cvt_pk_bf16_f32 v17, v22, v23
	v_lshl_add_u64 v[26:27], v[24:25], 0, v[0:1]
	ds_read2_b32 v[22:23], v9 offset0:8 offset1:41
	global_store_dwordx4 v[26:27], v[14:17], off sc1
	v_or_b32_e32 v0, s2, v18
	v_lshlrev_b32_e32 v0, 12, v0
	s_waitcnt lgkmcnt(0)
	v_cvt_pk_bf16_f32 v14, v22, v23
	ds_read2_b32 v[16:17], v9 offset0:74 offset1:107
	s_waitcnt lgkmcnt(0)
	v_cvt_pk_bf16_f32 v15, v16, v17
	ds_read2_b32 v[16:17], v9 offset0:140 offset1:173
	s_waitcnt lgkmcnt(0)
	v_cvt_pk_bf16_f32 v16, v16, v17
	ds_read2_b32 v[22:23], v9 offset0:206 offset1:239
	s_waitcnt lgkmcnt(0)
	v_cvt_pk_bf16_f32 v17, v22, v23
	v_lshl_add_u64 v[26:27], v[24:25], 0, v[0:1]
	ds_read2_b32 v[22:23], v9 offset0:16 offset1:49
	global_store_dwordx4 v[26:27], v[14:17], off sc1
	v_or_b32_e32 v0, s2, v19
	v_lshlrev_b32_e32 v0, 12, v0
	s_waitcnt lgkmcnt(0)
	v_cvt_pk_bf16_f32 v14, v22, v23
	ds_read2_b32 v[16:17], v9 offset0:82 offset1:115
	s_waitcnt lgkmcnt(0)
	v_cvt_pk_bf16_f32 v15, v16, v17
	ds_read2_b32 v[16:17], v9 offset0:148 offset1:181
	s_waitcnt lgkmcnt(0)
	v_cvt_pk_bf16_f32 v16, v16, v17
	ds_read2_b32 v[22:23], v9 offset0:214 offset1:247
	s_waitcnt lgkmcnt(0)
	v_cvt_pk_bf16_f32 v17, v22, v23
	v_lshl_add_u64 v[26:27], v[24:25], 0, v[0:1]
	ds_read2_b32 v[22:23], v9 offset0:24 offset1:57
	global_store_dwordx4 v[26:27], v[14:17], off sc1
	v_or_b32_e32 v0, s2, v20
	v_lshlrev_b32_e32 v0, 12, v0
	s_waitcnt lgkmcnt(0)
	v_cvt_pk_bf16_f32 v14, v22, v23
	ds_read2_b32 v[16:17], v9 offset0:90 offset1:123
	s_waitcnt lgkmcnt(0)
	v_cvt_pk_bf16_f32 v15, v16, v17
	ds_read2_b32 v[16:17], v9 offset0:156 offset1:189
	s_waitcnt lgkmcnt(0)
	v_cvt_pk_bf16_f32 v16, v16, v17
	ds_read2_b32 v[22:23], v9 offset0:222 offset1:255
	s_waitcnt lgkmcnt(0)
	v_cvt_pk_bf16_f32 v17, v22, v23
	v_lshl_add_u64 v[22:23], v[24:25], 0, v[0:1]
	global_store_dwordx4 v[22:23], v[14:17], off sc1
	s_waitcnt lgkmcnt(0)
	v_readlane_b32 s70, v253, 44
	v_readlane_b32 s71, v253, 45
	s_mov_b32 s48, 0x3a000000

;     ...
; #pragma unroll 8
;     for (int i = 0; i < 32; ++i) { const int kk = 2 * i + (lane >> 5); scr[kk * 33 + (lane & 31)] = W[(size_t)(k0 + kk) * N + n0 + (lane & 31)]; }
; __device__ __forceinline__ void phase_convert(const Args& a, LAS unsigned char* lds) {
;     ...
;         if (r < I_P) { transpose_item(a.in[I_PB] + (size_t)l * DB * D, DB, D, (bf16*)(ws + WS_WPAB) + (size_t)l * D * D, 1 << 30, scr, r, lane, D, DA); continue; } r -= I_P;
.LBB0_489:
	s_lshl_b32 s46, s43, 1
	s_lshl_b32 s45, s41, 1
	v_or_b32_e32 v0, s46, v16
	s_add_i32 s49, s46, 4
	s_add_i32 s48, s45, 4
	s_add_i32 s50, s45, 8
	s_add_i32 s51, s46, 8
	v_lshlrev_b64 v[40:41], 13, v[0:1]
	v_or_b32_e32 v0, s49, v16
	v_mov_b32_e32 v23, v1
	v_mov_b32_e32 v25, v1
	v_mov_b32_e32 v27, v1
	v_or_b32_e32 v22, s45, v5
	s_add_i32 s52, s45, 12
	s_add_i32 s53, s46, 12
	s_add_i32 s54, s45, 16
	s_add_i32 s56, s45, 20
	s_add_i32 s58, s45, 24
	s_add_i32 s60, s45, 28
	v_or_b32_e32 v24, s48, v5
	v_or_b32_e32 v26, s50, v5
	v_lshlrev_b64 v[42:43], 13, v[0:1]
	v_or_b32_e32 v0, s51, v16
	v_mov_b32_e32 v29, v1
	v_mov_b32_e32 v31, v1
	v_mov_b32_e32 v33, v1
	v_mov_b32_e32 v35, v1
	v_mov_b32_e32 v37, v1
	s_add_i32 s55, s46, 16
	v_lshlrev_b64 v[22:23], 13, v[22:23]
	v_or_b32_e32 v28, s52, v5
	v_or_b32_e32 v30, s54, v5
	v_or_b32_e32 v32, s56, v5
	v_or_b32_e32 v34, s58, v5
	v_or_b32_e32 v36, s60, v5
	v_lshl_add_u64 v[40:41], v[14:15], 0, v[40:41]
	v_lshlrev_b64 v[24:25], 13, v[24:25]
	v_lshlrev_b64 v[26:27], 13, v[26:27]
	v_lshlrev_b64 v[44:45], 13, v[0:1]
	v_or_b32_e32 v0, s53, v16
	s_add_i32 s57, s46, 20
	v_lshl_add_u64 v[22:23], v[14:15], 0, v[22:23]
	v_lshlrev_b64 v[28:29], 13, v[28:29]
	v_lshlrev_b64 v[30:31], 13, v[30:31]
	v_lshlrev_b64 v[32:33], 13, v[32:33]
	v_lshlrev_b64 v[34:35], 13, v[34:35]
	v_lshlrev_b64 v[36:37], 13, v[36:37]
	v_lshl_add_u64 v[42:43], v[14:15], 0, v[42:43]
	v_lshl_add_u64 v[24:25], v[14:15], 0, v[24:25]
	v_lshl_add_u64 v[26:27], v[14:15], 0, v[26:27]
	global_load_dword v17, v[40:41], off
	global_load_dword v21, v[22:23], off
	v_lshlrev_b64 v[40:41], 13, v[0:1]
	v_or_b32_e32 v0, s55, v16
	s_add_i32 s59, s46, 24
	v_lshl_add_u64 v[28:29], v[14:15], 0, v[28:29]
	v_lshl_add_u64 v[30:31], v[14:15], 0, v[30:31]
	v_lshl_add_u64 v[32:33], v[14:15], 0, v[32:33]
	v_lshl_add_u64 v[34:35], v[14:15], 0, v[34:35]
	v_lshl_add_u64 v[36:37], v[14:15], 0, v[36:37]
	global_load_dword v39, v[42:43], off
	global_load_dword v56, v[24:25], off
	global_load_dword v57, v[26:27], off
	global_load_dword v58, v[28:29], off
	global_load_dword v59, v[30:31], off
	global_load_dword v60, v[32:33], off
	global_load_dword v61, v[34:35], off
	global_load_dword v62, v[36:37], off
	v_lshl_add_u64 v[24:25], v[14:15], 0, v[40:41]
	v_lshlrev_b64 v[26:27], 13, v[0:1]
	v_or_b32_e32 v0, s57, v16
	s_add_i32 s61, s46, 28
	v_lshl_add_u64 v[22:23], v[14:15], 0, v[44:45]
	global_load_dword v63, v[24:25], off
	global_load_dword v64, v[22:23], off
	v_lshlrev_b64 v[24:25], 13, v[0:1]
	v_or_b32_e32 v0, s59, v16
	v_lshl_add_u64 v[22:23], v[14:15], 0, v[26:27]
	v_lshlrev_b64 v[26:27], 13, v[0:1]
	v_or_b32_e32 v0, s61, v16
	v_lshlrev_b64 v[28:29], 13, v[0:1]
	v_lshl_add_u64 v[28:29], v[14:15], 0, v[28:29]
	v_lshl_add_u64 v[24:25], v[14:15], 0, v[24:25]
	v_lshl_add_u64 v[26:27], v[14:15], 0, v[26:27]
	global_load_dword v0, v[28:29], off
	global_load_dword v65, v[26:27], off
	global_load_dword v66, v[24:25], off
	global_load_dword v67, v[22:23], off
	v_or_b32_e32 v214, s45, v3
	v_or_b32_e32 v215, s46, v2
	v_or_b32_e32 v216, s48, v3
	v_or_b32_e32 v217, s49, v2
	v_or_b32_e32 v218, s50, v3
	v_or_b32_e32 v219, s51, v2
	v_or_b32_e32 v220, s52, v3
	v_or_b32_e32 v221, s53, v2
	v_or_b32_e32 v222, s54, v3
	v_or_b32_e32 v223, s55, v2
	v_or_b32_e32 v224, s56, v3
	v_or_b32_e32 v225, s57, v2
	v_or_b32_e32 v226, s58, v3
	v_or_b32_e32 v227, s59, v2
	v_or_b32_e32 v228, s60, v3
	v_or_b32_e32 v229, s61, v2
	s_add_i32 s43, s43, 16
	s_add_i32 s41, s41, 16
	s_add_i32 s44, s44, -16
	s_cmp_lg_u32 s44, 0
	v_mov_b32_e32 v95, 0
	s_lshl_b32 s46, s43, 1
	s_lshl_b32 s45, s41, 1
	v_or_b32_e32 v94, s46, v16
	s_add_i32 s49, s46, 4
	s_add_i32 s48, s45, 4
	s_add_i32 s50, s45, 8
	s_add_i32 s51, s46, 8
	v_lshlrev_b64 v[118:119], 13, v[94:95]
	v_or_b32_e32 v94, s49, v16
	v_mov_b32_e32 v101, v95
	v_mov_b32_e32 v103, v95
	v_mov_b32_e32 v105, v95
	v_or_b32_e32 v100, s45, v5
	s_add_i32 s52, s45, 12
	s_add_i32 s53, s46, 12
	s_add_i32 s54, s45, 16
	s_add_i32 s56, s45, 20
	s_add_i32 s58, s45, 24
	s_add_i32 s60, s45, 28
	v_or_b32_e32 v102, s48, v5
	v_or_b32_e32 v104, s50, v5
	v_lshlrev_b64 v[120:121], 13, v[94:95]
	v_or_b32_e32 v94, s51, v16
	v_mov_b32_e32 v107, v95
	v_mov_b32_e32 v109, v95
	v_mov_b32_e32 v111, v95
	v_mov_b32_e32 v113, v95
	v_mov_b32_e32 v115, v95
	s_add_i32 s55, s46, 16
	v_lshlrev_b64 v[100:101], 13, v[100:101]
	v_or_b32_e32 v106, s52, v5
	v_or_b32_e32 v108, s54, v5
	v_or_b32_e32 v110, s56, v5
	v_or_b32_e32 v112, s58, v5
	v_or_b32_e32 v114, s60, v5
	v_lshl_add_u64 v[118:119], v[14:15], 0, v[118:119]
	v_lshlrev_b64 v[102:103], 13, v[102:103]
	v_lshlrev_b64 v[104:105], 13, v[104:105]
	v_lshlrev_b64 v[122:123], 13, v[94:95]
	v_or_b32_e32 v94, s53, v16
	s_add_i32 s57, s46, 20
	v_lshl_add_u64 v[100:101], v[14:15], 0, v[100:101]
	v_lshlrev_b64 v[106:107], 13, v[106:107]
	v_lshlrev_b64 v[108:109], 13, v[108:109]
	v_lshlrev_b64 v[110:111], 13, v[110:111]
	v_lshlrev_b64 v[112:113], 13, v[112:113]
	v_lshlrev_b64 v[114:115], 13, v[114:115]
	v_lshl_add_u64 v[120:121], v[14:15], 0, v[120:121]
	v_lshl_add_u64 v[102:103], v[14:15], 0, v[102:103]
	v_lshl_add_u64 v[104:105], v[14:15], 0, v[104:105]
	global_load_dword v97, v[118:119], off
	global_load_dword v99, v[100:101], off
	v_lshlrev_b64 v[118:119], 13, v[94:95]
	v_or_b32_e32 v94, s55, v16
	s_add_i32 s59, s46, 24
	v_lshl_add_u64 v[106:107], v[14:15], 0, v[106:107]
	v_lshl_add_u64 v[108:109], v[14:15], 0, v[108:109]
	v_lshl_add_u64 v[110:111], v[14:15], 0, v[110:111]
	v_lshl_add_u64 v[112:113], v[14:15], 0, v[112:113]
	v_lshl_add_u64 v[114:115], v[14:15], 0, v[114:115]
	global_load_dword v117, v[120:121], off
	global_load_dword v96, v[102:103], off
; __device__ __forceinline__ unsigned cvt_pk_bf16(float lo, float hi) { unsigned r; asm volatile("v_cvt_pk_bf16_f32 %0, %1, %2" : "=v"(r) : "v"(lo), "v"(hi)); return r; }
; #define LAS __attribute__((address_space(3)))
; #define LDS_WAIT() asm volatile("s_waitcnt lgkmcnt(0)" ::: "memory")
;     ...
;     for (int i = 0; i < 32; ++i) { const int kk = 2 * i + (lane >> 5); scr[kk * 33 + (lane & 31)] = W[(size_t)(k0 + kk) * N + n0 + (lane & 31)]; }
;     LDS_WAIT(); asm volatile("" ::: "memory");
;     const int c = lane & 7;
; #pragma unroll
;     for (int j = 0; j < 4; ++j) { const int n = (lane >> 3) + 8 * j; const LAS float* s = scr + (8 * c) * 33 + n;
;         u32x4 o; o.x = cvt_pk_bf16(s[0 * 33], s[1 * 33]); o.y = cvt_pk_bf16(s[2 * 33], s[3 * 33]); o.z = cvt_pk_bf16(s[4 * 33], s[5 * 33]); o.w = cvt_pk_bf16(s[6 * 33], s[7 * 33]);
;         *(u32x4*)(WT + (size_t)(dn0 + n) * ldo + koff + k0 + 8 * c) = o; }
;     LDS_WAIT(); asm volatile("" ::: "memory");
	global_load_dword v135, v[104:105], off
	global_load_dword v98, v[106:107], off
	global_load_dword v137, v[108:109], off
	global_load_dword v116, v[110:111], off
	global_load_dword v151, v[112:113], off
	global_load_dword v134, v[114:115], off
	v_lshl_add_u64 v[102:103], v[14:15], 0, v[118:119]
	v_lshlrev_b64 v[104:105], 13, v[94:95]
	v_or_b32_e32 v94, s57, v16
	s_add_i32 s61, s46, 28
	v_lshl_add_u64 v[100:101], v[14:15], 0, v[122:123]
	global_load_dword v153, v[102:103], off
	global_load_dword v136, v[100:101], off
	v_lshlrev_b64 v[102:103], 13, v[94:95]
	v_or_b32_e32 v94, s59, v16
	v_lshl_add_u64 v[100:101], v[14:15], 0, v[104:105]
	v_lshlrev_b64 v[104:105], 13, v[94:95]
	v_or_b32_e32 v94, s61, v16
	v_lshlrev_b64 v[106:107], 13, v[94:95]
	v_lshl_add_u64 v[106:107], v[14:15], 0, v[106:107]
	v_lshl_add_u64 v[102:103], v[14:15], 0, v[102:103]
	v_lshl_add_u64 v[104:105], v[14:15], 0, v[104:105]
	global_load_dword v94, v[106:107], off
	global_load_dword v155, v[104:105], off
	global_load_dword v138, v[102:103], off
	global_load_dword v157, v[100:101], off
	v_or_b32_e32 v150, s45, v3
	v_or_b32_e32 v159, s46, v2
	v_or_b32_e32 v152, s48, v3
	v_or_b32_e32 v161, s49, v2
	v_or_b32_e32 v154, s50, v3
	v_or_b32_e32 v163, s51, v2
	v_or_b32_e32 v156, s52, v3
	v_or_b32_e32 v165, s53, v2
	v_or_b32_e32 v158, s54, v3
	v_or_b32_e32 v167, s55, v2
	v_or_b32_e32 v160, s56, v3
	v_or_b32_e32 v169, s57, v2
	v_or_b32_e32 v162, s58, v3
	v_or_b32_e32 v183, s59, v2
	v_or_b32_e32 v164, s60, v3
	v_or_b32_e32 v185, s61, v2
	s_add_i32 s43, s43, 16
	s_add_i32 s41, s41, 16
	s_add_i32 s44, s44, -16
	s_cmp_lg_u32 s44, 0
	v_mad_u64_u32 v[22:23], s[46:47], v215, s85, v[6:7]
	v_mad_u64_u32 v[24:25], s[46:47], v214, s85, v[6:7]
	v_mad_u64_u32 v[26:27], s[46:47], v217, s85, v[6:7]
	v_mad_u64_u32 v[28:29], s[46:47], v216, s85, v[6:7]
	v_mad_u64_u32 v[30:31], s[46:47], v219, s85, v[6:7]
	v_mad_u64_u32 v[32:33], s[46:47], v218, s85, v[6:7]
	v_mad_u64_u32 v[34:35], s[46:47], v221, s85, v[6:7]
	v_mad_u64_u32 v[36:37], s[46:47], v220, s85, v[6:7]
	v_mad_u64_u32 v[40:41], s[46:47], v223, s85, v[6:7]
	v_mad_u64_u32 v[42:43], s[46:47], v222, s85, v[6:7]
	v_mad_u64_u32 v[44:45], s[46:47], v225, s85, v[6:7]
	v_mad_u64_u32 v[46:47], s[46:47], v224, s85, v[6:7]
	v_mad_u64_u32 v[48:49], s[46:47], v227, s85, v[6:7]
	v_mad_u64_u32 v[50:51], s[46:47], v226, s85, v[6:7]
	v_mad_u64_u32 v[52:53], s[46:47], v229, s85, v[6:7]
	v_mad_u64_u32 v[54:55], s[46:47], v228, s85, v[6:7]
	s_waitcnt vmcnt(31)
	ds_write_b32 v22, v17
	s_waitcnt vmcnt(30)
	ds_write_b32 v24, v21
	s_waitcnt vmcnt(29)
	ds_write_b32 v26, v39
	s_waitcnt vmcnt(28)
	ds_write_b32 v28, v56
	s_waitcnt vmcnt(20)
	ds_write_b32 v30, v64
	ds_write_b32 v32, v57
	ds_write_b32 v34, v63
	ds_write_b32 v36, v58
	s_waitcnt vmcnt(16)
	ds_write_b32 v40, v67
	ds_write_b32 v42, v59
	ds_write_b32 v44, v66
	ds_write_b32 v46, v60
	ds_write_b32 v48, v65
	ds_write_b32 v50, v61
	ds_write_b32 v52, v0
	ds_write_b32 v54, v62
	v_mad_u64_u32 v[100:101], s[46:47], v159, s85, v[6:7]
	v_mad_u64_u32 v[102:103], s[46:47], v150, s85, v[6:7]
	v_mad_u64_u32 v[104:105], s[46:47], v161, s85, v[6:7]
	v_mad_u64_u32 v[106:107], s[46:47], v152, s85, v[6:7]
	v_mad_u64_u32 v[108:109], s[46:47], v163, s85, v[6:7]
	v_mad_u64_u32 v[110:111], s[46:47], v154, s85, v[6:7]
	v_mad_u64_u32 v[112:113], s[46:47], v165, s85, v[6:7]
	v_mad_u64_u32 v[114:115], s[46:47], v156, s85, v[6:7]
	v_mad_u64_u32 v[118:119], s[46:47], v167, s85, v[6:7]
	v_mad_u64_u32 v[120:121], s[46:47], v158, s85, v[6:7]
	v_mad_u64_u32 v[122:123], s[46:47], v169, s85, v[6:7]
	v_mad_u64_u32 v[124:125], s[46:47], v160, s85, v[6:7]
	v_mad_u64_u32 v[126:127], s[46:47], v183, s85, v[6:7]
	v_mad_u64_u32 v[128:129], s[46:47], v162, s85, v[6:7]
	v_mad_u64_u32 v[130:131], s[46:47], v185, s85, v[6:7]
	v_mad_u64_u32 v[132:133], s[46:47], v164, s85, v[6:7]
	s_waitcnt vmcnt(15)
	ds_write_b32 v100, v97
	s_waitcnt vmcnt(14)
	ds_write_b32 v102, v99
	s_waitcnt vmcnt(13)
	ds_write_b32 v104, v117
	s_waitcnt vmcnt(12)
	ds_write_b32 v106, v96
	s_waitcnt vmcnt(4)
	ds_write_b32 v108, v136
	ds_write_b32 v110, v135
	ds_write_b32 v112, v153
	ds_write_b32 v114, v98
	s_waitcnt vmcnt(0)
	ds_write_b32 v118, v157
	ds_write_b32 v120, v137
	ds_write_b32 v122, v138
	ds_write_b32 v124, v116
	ds_write_b32 v126, v155
	ds_write_b32 v128, v151
	ds_write_b32 v130, v94
	ds_write_b32 v132, v134
	s_add_u32 s38, s28, s38
	s_waitcnt lgkmcnt(0)
	s_addc_u32 s39, s29, s39
	s_lshl_b32 s3, s3, 1
	s_add_u32 s38, s38, s3
	ds_read2_b32 v[14:15], v9 offset1:33
	v_lshlrev_b32_e32 v0, 1, v8
	s_addc_u32 s39, s39, 0
	s_waitcnt lgkmcnt(0)
	v_cvt_pk_bf16_f32 v14, v14, v15
	ds_read2_b32 v[16:17], v9 offset0:66 offset1:99
	v_or_b32_e32 v5, s2, v7
	v_lshl_add_u64 v[24:25], s[38:39], 0, v[0:1]
	s_mov_b64 s[38:39], 0xd400800
	s_waitcnt lgkmcnt(0)
	v_cvt_pk_bf16_f32 v15, v16, v17
	ds_read2_b32 v[16:17], v9 offset0:132 offset1:165
	v_lshlrev_b32_e32 v0, 12, v5
	v_lshl_add_u64 v[24:25], v[24:25], 0, s[38:39]
	s_waitcnt lgkmcnt(0)
	v_cvt_pk_bf16_f32 v16, v16, v17
	ds_read2_b32 v[22:23], v9 offset0:198 offset1:231
	s_waitcnt lgkmcnt(0)
	v_cvt_pk_bf16_f32 v17, v22, v23
	v_lshl_add_u64 v[26:27], v[24:25], 0, v[0:1]
	ds_read2_b32 v[22:23], v9 offset0:8 offset1:41
	global_store_dwordx4 v[26:27], v[14:17], off sc1
	v_or_b32_e32 v0, s2, v18
	v_lshlrev_b32_e32 v0, 12, v0
	s_waitcnt lgkmcnt(0)
	v_cvt_pk_bf16_f32 v14, v22, v23
	ds_read2_b32 v[16:17], v9 offset0:74 offset1:107
	s_waitcnt lgkmcnt(0)
	v_cvt_pk_bf16_f32 v15, v16, v17
	ds_read2_b32 v[16:17], v9 offset0:140 offset1:173
	s_waitcnt lgkmcnt(0)
	v_cvt_pk_bf16_f32 v16, v16, v17
	ds_read2_b32 v[22:23], v9 offset0:206 offset1:239
	s_waitcnt lgkmcnt(0)
	v_cvt_pk_bf16_f32 v17, v22, v23
	v_lshl_add_u64 v[26:27], v[24:25], 0, v[0:1]
	ds_read2_b32 v[22:23], v9 offset0:16 offset1:49
	global_store_dwordx4 v[26:27], v[14:17], off sc1
	v_or_b32_e32 v0, s2, v19
	v_lshlrev_b32_e32 v0, 12, v0
	s_waitcnt lgkmcnt(0)
	v_cvt_pk_bf16_f32 v14, v22, v23
	ds_read2_b32 v[16:17], v9 offset0:82 offset1:115
	s_waitcnt lgkmcnt(0)
	v_cvt_pk_bf16_f32 v15, v16, v17
	ds_read2_b32 v[16:17], v9 offset0:148 offset1:181
	s_waitcnt lgkmcnt(0)
	v_cvt_pk_bf16_f32 v16, v16, v17
	ds_read2_b32 v[22:23], v9 offset0:214 offset1:247
	s_waitcnt lgkmcnt(0)
	v_cvt_pk_bf16_f32 v17, v22, v23
	v_lshl_add_u64 v[26:27], v[24:25], 0, v[0:1]
	ds_read2_b32 v[22:23], v9 offset0:24 offset1:57
	global_store_dwordx4 v[26:27], v[14:17], off sc1
	v_or_b32_e32 v0, s2, v20
	v_lshlrev_b32_e32 v0, 12, v0
	s_waitcnt lgkmcnt(0)
	v_cvt_pk_bf16_f32 v14, v22, v23
	ds_read2_b32 v[16:17], v9 offset0:90 offset1:123
	s_waitcnt lgkmcnt(0)
	v_cvt_pk_bf16_f32 v15, v16, v17
	ds_read2_b32 v[16:17], v9 offset0:156 offset1:189
	s_waitcnt lgkmcnt(0)
	v_cvt_pk_bf16_f32 v16, v16, v17
	ds_read2_b32 v[22:23], v9 offset0:222 offset1:255
	s_waitcnt lgkmcnt(0)
	v_cvt_pk_bf16_f32 v17, v22, v23
	v_lshl_add_u64 v[22:23], v[24:25], 0, v[0:1]
	global_store_dwordx4 v[22:23], v[14:17], off sc1
	s_waitcnt lgkmcnt(0)
	v_readlane_b32 s70, v253, 44
	v_readlane_b32 s71, v253, 45
	s_mov_b32 s48, 0x3a000000

;     ...
; #pragma unroll 8
;     for (int i = 0; i < 32; ++i) { const int kk = 2 * i + (lane >> 5); scr[kk * 33 + (lane & 31)] = W[(size_t)(k0 + kk) * N + n0 + (lane & 31)]; }
; __device__ __forceinline__ void phase_convert(const Args& a, LAS unsigned char* lds) {
;     ...
;         if (r < I_O) { transpose_item(a.in[I_WOUT] + (size_t)l * D * D, D, D, (bf16*)(ws + WS_WOUT) + (size_t)l * D * D, 1 << 30, scr, r, lane); continue; } r -= I_O;
.LBB0_494:
	s_lshl_b32 s45, s41, 1
	s_lshl_b32 s44, s3, 1
	v_or_b32_e32 v0, s45, v16
	s_add_i32 s47, s45, 4
	s_add_i32 s46, s44, 4
	s_add_i32 s48, s44, 8
	s_add_i32 s49, s45, 8
	v_lshlrev_b64 v[40:41], 13, v[0:1]
	v_or_b32_e32 v0, s47, v16
	v_mov_b32_e32 v23, v1
	v_mov_b32_e32 v25, v1
	v_mov_b32_e32 v27, v1
	v_or_b32_e32 v22, s44, v5
	s_add_i32 s50, s44, 12
	s_add_i32 s51, s45, 12
	s_add_i32 s52, s44, 16
	s_add_i32 s54, s44, 20
	s_add_i32 s56, s44, 24
	s_add_i32 s58, s44, 28
	v_or_b32_e32 v24, s46, v5
	v_or_b32_e32 v26, s48, v5
	v_lshlrev_b64 v[42:43], 13, v[0:1]
	v_or_b32_e32 v0, s49, v16
	v_mov_b32_e32 v29, v1
	v_mov_b32_e32 v31, v1
	v_mov_b32_e32 v33, v1
	v_mov_b32_e32 v35, v1
	v_mov_b32_e32 v37, v1
	s_add_i32 s53, s45, 16
	v_lshlrev_b64 v[22:23], 13, v[22:23]
	v_or_b32_e32 v28, s50, v5
	v_or_b32_e32 v30, s52, v5
	v_or_b32_e32 v32, s54, v5
	v_or_b32_e32 v34, s56, v5
	v_or_b32_e32 v36, s58, v5
	v_lshl_add_u64 v[40:41], v[14:15], 0, v[40:41]
	v_lshlrev_b64 v[24:25], 13, v[24:25]
	v_lshlrev_b64 v[26:27], 13, v[26:27]
	v_lshlrev_b64 v[44:45], 13, v[0:1]
	v_or_b32_e32 v0, s51, v16
	s_add_i32 s55, s45, 20
	v_lshl_add_u64 v[22:23], v[14:15], 0, v[22:23]
	v_lshlrev_b64 v[28:29], 13, v[28:29]
	v_lshlrev_b64 v[30:31], 13, v[30:31]
	v_lshlrev_b64 v[32:33], 13, v[32:33]
	v_lshlrev_b64 v[34:35], 13, v[34:35]
	v_lshlrev_b64 v[36:37], 13, v[36:37]
	v_lshl_add_u64 v[42:43], v[14:15], 0, v[42:43]
	v_lshl_add_u64 v[24:25], v[14:15], 0, v[24:25]
	v_lshl_add_u64 v[26:27], v[14:15], 0, v[26:27]
	global_load_dword v17, v[40:41], off
	global_load_dword v21, v[22:23], off
	v_lshlrev_b64 v[40:41], 13, v[0:1]
	v_or_b32_e32 v0, s53, v16
	s_add_i32 s57, s45, 24
	v_lshl_add_u64 v[28:29], v[14:15], 0, v[28:29]
	v_lshl_add_u64 v[30:31], v[14:15], 0, v[30:31]
	v_lshl_add_u64 v[32:33], v[14:15], 0, v[32:33]
	v_lshl_add_u64 v[34:35], v[14:15], 0, v[34:35]
	v_lshl_add_u64 v[36:37], v[14:15], 0, v[36:37]
	global_load_dword v39, v[42:43], off
	global_load_dword v56, v[24:25], off
	global_load_dword v57, v[26:27], off
	global_load_dword v58, v[28:29], off
	global_load_dword v59, v[30:31], off
	global_load_dword v60, v[32:33], off
	global_load_dword v61, v[34:35], off
	global_load_dword v62, v[36:37], off
	v_lshl_add_u64 v[24:25], v[14:15], 0, v[40:41]
	v_lshlrev_b64 v[26:27], 13, v[0:1]
	v_or_b32_e32 v0, s55, v16
	s_add_i32 s59, s45, 28
	v_lshl_add_u64 v[22:23], v[14:15], 0, v[44:45]
	global_load_dword v63, v[24:25], off
	global_load_dword v64, v[22:23], off
	v_lshlrev_b64 v[24:25], 13, v[0:1]
	v_or_b32_e32 v0, s57, v16
	v_lshl_add_u64 v[22:23], v[14:15], 0, v[26:27]
	v_lshlrev_b64 v[26:27], 13, v[0:1]
	v_or_b32_e32 v0, s59, v16
	v_lshlrev_b64 v[28:29], 13, v[0:1]
	v_lshl_add_u64 v[28:29], v[14:15], 0, v[28:29]
	v_lshl_add_u64 v[24:25], v[14:15], 0, v[24:25]
	v_lshl_add_u64 v[26:27], v[14:15], 0, v[26:27]
	global_load_dword v0, v[28:29], off
	global_load_dword v65, v[26:27], off
	global_load_dword v66, v[24:25], off
	global_load_dword v67, v[22:23], off
	v_or_b32_e32 v214, s44, v3
	v_or_b32_e32 v215, s45, v2
	v_or_b32_e32 v216, s46, v3
	v_or_b32_e32 v217, s47, v2
	v_or_b32_e32 v218, s48, v3
	v_or_b32_e32 v219, s49, v2
	v_or_b32_e32 v220, s50, v3
	v_or_b32_e32 v221, s51, v2
	v_or_b32_e32 v222, s52, v3
	v_or_b32_e32 v223, s53, v2
	v_or_b32_e32 v224, s54, v3
	v_or_b32_e32 v225, s55, v2
	v_or_b32_e32 v226, s56, v3
	v_or_b32_e32 v227, s57, v2
	v_or_b32_e32 v228, s58, v3
	v_or_b32_e32 v229, s59, v2
	s_add_i32 s41, s41, 16
	s_add_i32 s3, s3, 16
	s_add_i32 s43, s43, -16
	s_cmp_lg_u32 s43, 0
	v_mov_b32_e32 v95, 0
	s_lshl_b32 s45, s41, 1
	s_lshl_b32 s44, s3, 1
	v_or_b32_e32 v94, s45, v16
	s_add_i32 s47, s45, 4
	s_add_i32 s46, s44, 4
	s_add_i32 s48, s44, 8
	s_add_i32 s49, s45, 8
	v_lshlrev_b64 v[118:119], 13, v[94:95]
	v_or_b32_e32 v94, s47, v16
	v_mov_b32_e32 v101, v95
	v_mov_b32_e32 v103, v95
	v_mov_b32_e32 v105, v95
	v_or_b32_e32 v100, s44, v5
	s_add_i32 s50, s44, 12
	s_add_i32 s51, s45, 12
	s_add_i32 s52, s44, 16
	s_add_i32 s54, s44, 20
	s_add_i32 s56, s44, 24
	s_add_i32 s58, s44, 28
	v_or_b32_e32 v102, s46, v5
	v_or_b32_e32 v104, s48, v5
	v_lshlrev_b64 v[120:121], 13, v[94:95]
	v_or_b32_e32 v94, s49, v16
	v_mov_b32_e32 v107, v95
	v_mov_b32_e32 v109, v95
	v_mov_b32_e32 v111, v95
	v_mov_b32_e32 v113, v95
	v_mov_b32_e32 v115, v95
	s_add_i32 s53, s45, 16
	v_lshlrev_b64 v[100:101], 13, v[100:101]
	v_or_b32_e32 v106, s50, v5
	v_or_b32_e32 v108, s52, v5
	v_or_b32_e32 v110, s54, v5
	v_or_b32_e32 v112, s56, v5
	v_or_b32_e32 v114, s58, v5
	v_lshl_add_u64 v[118:119], v[14:15], 0, v[118:119]
	v_lshlrev_b64 v[102:103], 13, v[102:103]
	v_lshlrev_b64 v[104:105], 13, v[104:105]
	v_lshlrev_b64 v[122:123], 13, v[94:95]
	v_or_b32_e32 v94, s51, v16
	s_add_i32 s55, s45, 20
	v_lshl_add_u64 v[100:101], v[14:15], 0, v[100:101]
	v_lshlrev_b64 v[106:107], 13, v[106:107]
	v_lshlrev_b64 v[108:109], 13, v[108:109]
	v_lshlrev_b64 v[110:111], 13, v[110:111]
	v_lshlrev_b64 v[112:113], 13, v[112:113]
	v_lshlrev_b64 v[114:115], 13, v[114:115]
	v_lshl_add_u64 v[120:121], v[14:15], 0, v[120:121]
	v_lshl_add_u64 v[102:103], v[14:15], 0, v[102:103]
	v_lshl_add_u64 v[104:105], v[14:15], 0, v[104:105]
	global_load_dword v97, v[118:119], off
	global_load_dword v99, v[100:101], off
	v_lshlrev_b64 v[118:119], 13, v[94:95]
	v_or_b32_e32 v94, s53, v16
	s_add_i32 s57, s45, 24
	v_lshl_add_u64 v[106:107], v[14:15], 0, v[106:107]
	v_lshl_add_u64 v[108:109], v[14:15], 0, v[108:109]
	v_lshl_add_u64 v[110:111], v[14:15], 0, v[110:111]
	v_lshl_add_u64 v[112:113], v[14:15], 0, v[112:113]
	v_lshl_add_u64 v[114:115], v[14:15], 0, v[114:115]
	global_load_dword v117, v[120:121], off
	global_load_dword v96, v[102:103], off
; __device__ __forceinline__ unsigned cvt_pk_bf16(float lo, float hi) { unsigned r; asm volatile("v_cvt_pk_bf16_f32 %0, %1, %2" : "=v"(r) : "v"(lo), "v"(hi)); return r; }
; #define LAS __attribute__((address_space(3)))
; #define LDS_WAIT() asm volatile("s_waitcnt lgkmcnt(0)" ::: "memory")
;     ...
;     for (int i = 0; i < 32; ++i) { const int kk = 2 * i + (lane >> 5); scr[kk * 33 + (lane & 31)] = W[(size_t)(k0 + kk) * N + n0 + (lane & 31)]; }
;     LDS_WAIT(); asm volatile("" ::: "memory");
;     const int c = lane & 7;
; #pragma unroll
;     for (int j = 0; j < 4; ++j) { const int n = (lane >> 3) + 8 * j; const LAS float* s = scr + (8 * c) * 33 + n;
;         u32x4 o; o.x = cvt_pk_bf16(s[0 * 33], s[1 * 33]); o.y = cvt_pk_bf16(s[2 * 33], s[3 * 33]); o.z = cvt_pk_bf16(s[4 * 33], s[5 * 33]); o.w = cvt_pk_bf16(s[6 * 33], s[7 * 33]);
;         *(u32x4*)(WT + (size_t)(dn0 + n) * ldo + koff + k0 + 8 * c) = o; }
;     LDS_WAIT(); asm volatile("" ::: "memory");
	global_load_dword v135, v[104:105], off
	global_load_dword v98, v[106:107], off
	global_load_dword v137, v[108:109], off
	global_load_dword v116, v[110:111], off
	global_load_dword v151, v[112:113], off
	global_load_dword v134, v[114:115], off
	v_lshl_add_u64 v[102:103], v[14:15], 0, v[118:119]
	v_lshlrev_b64 v[104:105], 13, v[94:95]
	v_or_b32_e32 v94, s55, v16
	s_add_i32 s59, s45, 28
	v_lshl_add_u64 v[100:101], v[14:15], 0, v[122:123]
	global_load_dword v153, v[102:103], off
	global_load_dword v136, v[100:101], off
	v_lshlrev_b64 v[102:103], 13, v[94:95]
	v_or_b32_e32 v94, s57, v16
	v_lshl_add_u64 v[100:101], v[14:15], 0, v[104:105]
	v_lshlrev_b64 v[104:105], 13, v[94:95]
	v_or_b32_e32 v94, s59, v16
	v_lshlrev_b64 v[106:107], 13, v[94:95]
	v_lshl_add_u64 v[106:107], v[14:15], 0, v[106:107]
	v_lshl_add_u64 v[102:103], v[14:15], 0, v[102:103]
	v_lshl_add_u64 v[104:105], v[14:15], 0, v[104:105]
	global_load_dword v94, v[106:107], off
	global_load_dword v155, v[104:105], off
	global_load_dword v138, v[102:103], off
	global_load_dword v157, v[100:101], off
	v_or_b32_e32 v150, s44, v3
	v_or_b32_e32 v159, s45, v2
	v_or_b32_e32 v152, s46, v3
	v_or_b32_e32 v161, s47, v2
	v_or_b32_e32 v154, s48, v3
	v_or_b32_e32 v163, s49, v2
	v_or_b32_e32 v156, s50, v3
	v_or_b32_e32 v165, s51, v2
	v_or_b32_e32 v158, s52, v3
	v_or_b32_e32 v167, s53, v2
	v_or_b32_e32 v160, s54, v3
	v_or_b32_e32 v169, s55, v2
	v_or_b32_e32 v162, s56, v3
	v_or_b32_e32 v183, s57, v2
	v_or_b32_e32 v164, s58, v3
	v_or_b32_e32 v185, s59, v2
	s_add_i32 s41, s41, 16
	s_add_i32 s3, s3, 16
	s_add_i32 s43, s43, -16
	s_cmp_lg_u32 s43, 0
	v_mad_u64_u32 v[22:23], s[44:45], v215, s85, v[6:7]
	v_mad_u64_u32 v[24:25], s[44:45], v214, s85, v[6:7]
	v_mad_u64_u32 v[26:27], s[44:45], v217, s85, v[6:7]
	v_mad_u64_u32 v[28:29], s[44:45], v216, s85, v[6:7]
	v_mad_u64_u32 v[30:31], s[44:45], v219, s85, v[6:7]
	v_mad_u64_u32 v[32:33], s[44:45], v218, s85, v[6:7]
	v_mad_u64_u32 v[34:35], s[44:45], v221, s85, v[6:7]
	v_mad_u64_u32 v[36:37], s[44:45], v220, s85, v[6:7]
	v_mad_u64_u32 v[40:41], s[44:45], v223, s85, v[6:7]
	v_mad_u64_u32 v[42:43], s[44:45], v222, s85, v[6:7]
	v_mad_u64_u32 v[44:45], s[44:45], v225, s85, v[6:7]
	v_mad_u64_u32 v[46:47], s[44:45], v224, s85, v[6:7]
	v_mad_u64_u32 v[48:49], s[44:45], v227, s85, v[6:7]
	v_mad_u64_u32 v[50:51], s[44:45], v226, s85, v[6:7]
	v_mad_u64_u32 v[52:53], s[44:45], v229, s85, v[6:7]
	v_mad_u64_u32 v[54:55], s[44:45], v228, s85, v[6:7]
	s_waitcnt vmcnt(31)
	ds_write_b32 v22, v17
	s_waitcnt vmcnt(30)
	ds_write_b32 v24, v21
	s_waitcnt vmcnt(29)
	ds_write_b32 v26, v39
	s_waitcnt vmcnt(28)
	ds_write_b32 v28, v56
	s_waitcnt vmcnt(20)
	ds_write_b32 v30, v64
	ds_write_b32 v32, v57
	ds_write_b32 v34, v63
	ds_write_b32 v36, v58
	s_waitcnt vmcnt(16)
	ds_write_b32 v40, v67
	ds_write_b32 v42, v59
	ds_write_b32 v44, v66
	ds_write_b32 v46, v60
	ds_write_b32 v48, v65
	ds_write_b32 v50, v61
	ds_write_b32 v52, v0
	ds_write_b32 v54, v62
	v_mad_u64_u32 v[100:101], s[44:45], v159, s85, v[6:7]
	v_mad_u64_u32 v[102:103], s[44:45], v150, s85, v[6:7]
	v_mad_u64_u32 v[104:105], s[44:45], v161, s85, v[6:7]
	v_mad_u64_u32 v[106:107], s[44:45], v152, s85, v[6:7]
	v_mad_u64_u32 v[108:109], s[44:45], v163, s85, v[6:7]
	v_mad_u64_u32 v[110:111], s[44:45], v154, s85, v[6:7]
	v_mad_u64_u32 v[112:113], s[44:45], v165, s85, v[6:7]
	v_mad_u64_u32 v[114:115], s[44:45], v156, s85, v[6:7]
	v_mad_u64_u32 v[118:119], s[44:45], v167, s85, v[6:7]
	v_mad_u64_u32 v[120:121], s[44:45], v158, s85, v[6:7]
	v_mad_u64_u32 v[122:123], s[44:45], v169, s85, v[6:7]
	v_mad_u64_u32 v[124:125], s[44:45], v160, s85, v[6:7]
	v_mad_u64_u32 v[126:127], s[44:45], v183, s85, v[6:7]
	v_mad_u64_u32 v[128:129], s[44:45], v162, s85, v[6:7]
	v_mad_u64_u32 v[130:131], s[44:45], v185, s85, v[6:7]
	v_mad_u64_u32 v[132:133], s[44:45], v164, s85, v[6:7]
	s_waitcnt vmcnt(15)
	ds_write_b32 v100, v97
	s_waitcnt vmcnt(14)
	ds_write_b32 v102, v99
	s_waitcnt vmcnt(13)
	ds_write_b32 v104, v117
	s_waitcnt vmcnt(12)
	ds_write_b32 v106, v96
	s_waitcnt vmcnt(4)
	ds_write_b32 v108, v136
	ds_write_b32 v110, v135
	ds_write_b32 v112, v153
	ds_write_b32 v114, v98
	s_waitcnt vmcnt(0)
	ds_write_b32 v118, v157
	ds_write_b32 v120, v137
	ds_write_b32 v122, v138
	ds_write_b32 v124, v116
	ds_write_b32 v126, v155
	ds_write_b32 v128, v151
	ds_write_b32 v130, v94
	ds_write_b32 v132, v134
	v_readlane_b32 s3, v251, 20
	s_waitcnt lgkmcnt(0)
	s_add_u32 s3, s3, s38
	v_readlane_b32 s38, v251, 21
	s_addc_u32 s38, s38, s39
	s_lshl_b32 s2, s2, 1
	ds_read2_b32 v[14:15], v9 offset1:33
	s_add_u32 s2, s3, s2
	s_waitcnt lgkmcnt(0)
	v_cvt_pk_bf16_f32 v14, v14, v15
	ds_read2_b32 v[16:17], v9 offset0:66 offset1:99
	v_lshlrev_b32_e32 v0, 1, v8
	v_or_b32_e32 v5, s1, v7
	s_addc_u32 s3, s38, 0
	s_waitcnt lgkmcnt(0)
	v_cvt_pk_bf16_f32 v15, v16, v17
	ds_read2_b32 v[16:17], v9 offset0:132 offset1:165
	v_lshl_add_u64 v[24:25], s[2:3], 0, v[0:1]
	v_lshlrev_b32_e32 v0, 12, v5
	s_waitcnt lgkmcnt(0)
	v_cvt_pk_bf16_f32 v16, v16, v17
	ds_read2_b32 v[22:23], v9 offset0:198 offset1:231
	s_waitcnt lgkmcnt(0)
	v_cvt_pk_bf16_f32 v17, v22, v23
	v_lshl_add_u64 v[26:27], v[24:25], 0, v[0:1]
	ds_read2_b32 v[22:23], v9 offset0:8 offset1:41
	global_store_dwordx4 v[26:27], v[14:17], off sc1
	v_or_b32_e32 v0, s1, v18
	v_lshlrev_b32_e32 v0, 12, v0
	s_waitcnt lgkmcnt(0)
	v_cvt_pk_bf16_f32 v14, v22, v23
	ds_read2_b32 v[16:17], v9 offset0:74 offset1:107
	s_waitcnt lgkmcnt(0)
	v_cvt_pk_bf16_f32 v15, v16, v17
	ds_read2_b32 v[16:17], v9 offset0:140 offset1:173
	s_waitcnt lgkmcnt(0)
	v_cvt_pk_bf16_f32 v16, v16, v17
	ds_read2_b32 v[22:23], v9 offset0:206 offset1:239
	s_waitcnt lgkmcnt(0)
	v_cvt_pk_bf16_f32 v17, v22, v23
	v_lshl_add_u64 v[26:27], v[24:25], 0, v[0:1]
	ds_read2_b32 v[22:23], v9 offset0:16 offset1:49
	global_store_dwordx4 v[26:27], v[14:17], off sc1
	v_or_b32_e32 v0, s1, v19
	v_lshlrev_b32_e32 v0, 12, v0
	s_waitcnt lgkmcnt(0)
	v_cvt_pk_bf16_f32 v14, v22, v23
	ds_read2_b32 v[16:17], v9 offset0:82 offset1:115
	s_waitcnt lgkmcnt(0)
	v_cvt_pk_bf16_f32 v15, v16, v17
	ds_read2_b32 v[16:17], v9 offset0:148 offset1:181
	s_waitcnt lgkmcnt(0)
	v_cvt_pk_bf16_f32 v16, v16, v17
	ds_read2_b32 v[22:23], v9 offset0:214 offset1:247
	s_waitcnt lgkmcnt(0)
	v_cvt_pk_bf16_f32 v17, v22, v23
	v_lshl_add_u64 v[26:27], v[24:25], 0, v[0:1]
	ds_read2_b32 v[22:23], v9 offset0:24 offset1:57
	global_store_dwordx4 v[26:27], v[14:17], off sc1
	v_or_b32_e32 v0, s1, v20
	v_lshlrev_b32_e32 v0, 12, v0
	s_waitcnt lgkmcnt(0)
	v_cvt_pk_bf16_f32 v14, v22, v23
	ds_read2_b32 v[16:17], v9 offset0:90 offset1:123
	s_waitcnt lgkmcnt(0)
	v_cvt_pk_bf16_f32 v15, v16, v17
	ds_read2_b32 v[16:17], v9 offset0:156 offset1:189
	s_waitcnt lgkmcnt(0)
	v_cvt_pk_bf16_f32 v16, v16, v17
	ds_read2_b32 v[22:23], v9 offset0:222 offset1:255
	s_waitcnt lgkmcnt(0)
	v_cvt_pk_bf16_f32 v17, v22, v23
	v_lshl_add_u64 v[22:23], v[24:25], 0, v[0:1]
	global_store_dwordx4 v[22:23], v[14:17], off sc1
	s_waitcnt lgkmcnt(0)
	s_mov_b32 s48, 0x3a000000

;     ...
; #pragma unroll 8
;     for (int i = 0; i < 32; ++i) { const int kk = 2 * i + (lane >> 5); scr[kk * 33 + (lane & 31)] = W[(size_t)(k0 + kk) * N + n0 + (lane & 31)]; }
; __device__ __forceinline__ void phase_convert(const Args& a, LAS unsigned char* lds) {
;     ...
;         if (r < I_IN) { transpose_item(a.in[I_WIN] + (size_t)l * D * NIN, D, NIN, (bf16*)(ws + WS_WIN + l * SZ_WIN), 3200, scr, r, lane); continue; } r -= I_IN;
.LBB0_498:
	s_lshl_b32 s41, s2, 1
	s_lshl_b32 s43, s3, 1
	v_or_b32_e32 v21, s41, v5
	v_or_b32_e32 v16, s43, v0
	s_add_i32 s46, s41, 4
	s_add_i32 s47, s43, 4
	s_add_i32 s48, s41, 8
	s_add_i32 s49, s43, 8
	s_add_i32 s50, s41, 12
	s_add_i32 s51, s43, 12
	s_add_i32 s52, s41, 16
	s_add_i32 s53, s43, 16
	s_add_i32 s54, s41, 20
	s_add_i32 s55, s43, 20
	s_add_i32 s56, s41, 24
	s_add_i32 s57, s43, 24
	s_add_i32 s58, s41, 28
	s_add_i32 s59, s43, 28
	v_mad_i64_i32 v[16:17], s[44:45], v16, s6, v[14:15]
	v_mad_i64_i32 v[22:23], s[44:45], v21, s6, v[14:15]
	v_or_b32_e32 v21, s46, v5
	v_or_b32_e32 v24, s47, v0
	v_or_b32_e32 v30, s48, v5
	v_or_b32_e32 v28, s49, v0
	v_or_b32_e32 v34, s50, v5
	v_or_b32_e32 v32, s51, v0
	v_or_b32_e32 v39, s52, v5
	v_or_b32_e32 v36, s53, v0
	v_or_b32_e32 v44, s54, v5
	v_or_b32_e32 v42, s55, v0
	v_or_b32_e32 v48, s56, v5
	v_or_b32_e32 v46, s57, v0
	v_or_b32_e32 v52, s58, v5
	v_or_b32_e32 v50, s59, v0
	v_mad_i64_i32 v[24:25], s[44:45], v24, s6, v[14:15]
	v_mad_i64_i32 v[26:27], s[44:45], v21, s6, v[14:15]
	v_mad_i64_i32 v[28:29], s[44:45], v28, s6, v[14:15]
	v_mad_i64_i32 v[30:31], s[44:45], v30, s6, v[14:15]
	v_mad_i64_i32 v[32:33], s[44:45], v32, s6, v[14:15]
	v_mad_i64_i32 v[34:35], s[44:45], v34, s6, v[14:15]
	v_mad_i64_i32 v[36:37], s[44:45], v36, s6, v[14:15]
	v_mad_i64_i32 v[40:41], s[44:45], v39, s6, v[14:15]
	v_mad_i64_i32 v[42:43], s[44:45], v42, s6, v[14:15]
	v_mad_i64_i32 v[44:45], s[44:45], v44, s6, v[14:15]
	v_mad_i64_i32 v[46:47], s[44:45], v46, s6, v[14:15]
	v_mad_i64_i32 v[48:49], s[44:45], v48, s6, v[14:15]
	v_mad_i64_i32 v[50:51], s[44:45], v50, s6, v[14:15]
	v_mad_i64_i32 v[52:53], s[44:45], v52, s6, v[14:15]
	global_load_dword v21, v[16:17], off
	global_load_dword v39, v[22:23], off
	global_load_dword v54, v[24:25], off
	global_load_dword v55, v[26:27], off
	global_load_dword v56, v[28:29], off
	global_load_dword v57, v[30:31], off
	global_load_dword v58, v[32:33], off
	global_load_dword v59, v[34:35], off
	global_load_dword v60, v[36:37], off
	global_load_dword v61, v[40:41], off
	global_load_dword v62, v[42:43], off
	global_load_dword v63, v[44:45], off
	global_load_dword v64, v[46:47], off
	global_load_dword v65, v[48:49], off
	global_load_dword v66, v[50:51], off
	global_load_dword v67, v[52:53], off
	v_or_b32_e32 v214, s41, v3
	v_or_b32_e32 v215, s43, v2
	v_or_b32_e32 v216, s46, v3
	v_or_b32_e32 v217, s47, v2
	v_or_b32_e32 v218, s48, v3
	v_or_b32_e32 v219, s49, v2
	v_or_b32_e32 v220, s50, v3
	v_or_b32_e32 v221, s51, v2
	v_or_b32_e32 v222, s52, v3
	v_or_b32_e32 v223, s53, v2
	v_or_b32_e32 v224, s54, v3
	v_or_b32_e32 v225, s55, v2
	v_or_b32_e32 v226, s56, v3
	v_or_b32_e32 v227, s57, v2
	v_or_b32_e32 v228, s58, v3
	v_or_b32_e32 v229, s59, v2
	s_add_i32 s3, s3, 16
	s_add_i32 s2, s2, 16
	s_add_i32 s39, s39, -16
	s_cmp_lg_u32 s39, 0
	s_lshl_b32 s41, s2, 1
	s_lshl_b32 s43, s3, 1
	v_or_b32_e32 v97, s41, v5
	v_or_b32_e32 v94, s43, v0
	s_add_i32 s46, s41, 4
	s_add_i32 s47, s43, 4
	s_add_i32 s48, s41, 8
	s_add_i32 s49, s43, 8
	s_add_i32 s50, s41, 12
	s_add_i32 s51, s43, 12
	s_add_i32 s52, s41, 16
	s_add_i32 s53, s43, 16
	s_add_i32 s54, s41, 20
	s_add_i32 s55, s43, 20
	s_add_i32 s56, s41, 24
	s_add_i32 s57, s43, 24
	s_add_i32 s58, s41, 28
	s_add_i32 s59, s43, 28
	v_mad_i64_i32 v[94:95], s[44:45], v94, s6, v[14:15]
	v_mad_i64_i32 v[98:99], s[44:45], v97, s6, v[14:15]
	v_or_b32_e32 v97, s46, v5
	v_or_b32_e32 v100, s47, v0
	v_or_b32_e32 v106, s48, v5
	v_or_b32_e32 v104, s49, v0
	v_or_b32_e32 v110, s50, v5
	v_or_b32_e32 v108, s51, v0
	v_or_b32_e32 v115, s52, v5
	v_or_b32_e32 v112, s53, v0
	v_or_b32_e32 v120, s54, v5
	v_or_b32_e32 v118, s55, v0
	v_or_b32_e32 v124, s56, v5
	v_or_b32_e32 v122, s57, v0
	v_or_b32_e32 v128, s58, v5
	v_or_b32_e32 v126, s59, v0
	v_mad_i64_i32 v[100:101], s[44:45], v100, s6, v[14:15]
	v_mad_i64_i32 v[102:103], s[44:45], v97, s6, v[14:15]
	v_mad_i64_i32 v[104:105], s[44:45], v104, s6, v[14:15]
	v_mad_i64_i32 v[106:107], s[44:45], v106, s6, v[14:15]
	v_mad_i64_i32 v[108:109], s[44:45], v108, s6, v[14:15]
	v_mad_i64_i32 v[110:111], s[44:45], v110, s6, v[14:15]
	v_mad_i64_i32 v[112:113], s[44:45], v112, s6, v[14:15]
	v_mad_i64_i32 v[116:117], s[44:45], v115, s6, v[14:15]
	v_mad_i64_i32 v[118:119], s[44:45], v118, s6, v[14:15]
	v_mad_i64_i32 v[120:121], s[44:45], v120, s6, v[14:15]
	v_mad_i64_i32 v[122:123], s[44:45], v122, s6, v[14:15]
	v_mad_i64_i32 v[124:125], s[44:45], v124, s6, v[14:15]
	v_mad_i64_i32 v[126:127], s[44:45], v126, s6, v[14:15]
	v_mad_i64_i32 v[128:129], s[44:45], v128, s6, v[14:15]
	global_load_dword v97, v[94:95], off
	global_load_dword v115, v[98:99], off
	global_load_dword v96, v[100:101], off
	global_load_dword v131, v[102:103], off
	global_load_dword v114, v[104:105], off
	global_load_dword v133, v[106:107], off
	global_load_dword v130, v[108:109], off
	global_load_dword v135, v[110:111], off
	global_load_dword v132, v[112:113], off
	global_load_dword v137, v[116:117], off
	global_load_dword v134, v[118:119], off
	global_load_dword v151, v[120:121], off
	global_load_dword v136, v[122:123], off
	global_load_dword v153, v[124:125], off
	global_load_dword v138, v[126:127], off
	global_load_dword v155, v[128:129], off
	v_or_b32_e32 v150, s41, v3
	v_or_b32_e32 v157, s43, v2
	v_or_b32_e32 v152, s46, v3
	v_or_b32_e32 v159, s47, v2
	v_or_b32_e32 v154, s48, v3
	v_or_b32_e32 v161, s49, v2
	v_or_b32_e32 v156, s50, v3
	v_or_b32_e32 v163, s51, v2
	v_or_b32_e32 v158, s52, v3
	v_or_b32_e32 v165, s53, v2
	v_or_b32_e32 v160, s54, v3
	v_or_b32_e32 v167, s55, v2
	v_or_b32_e32 v162, s56, v3
	v_or_b32_e32 v169, s57, v2
	v_or_b32_e32 v164, s58, v3
	v_or_b32_e32 v183, s59, v2
	s_add_i32 s3, s3, 16
	s_add_i32 s2, s2, 16
	s_add_i32 s39, s39, -16
	s_cmp_lg_u32 s39, 0
	v_mad_u64_u32 v[16:17], s[44:45], v215, s85, v[6:7]
	v_mad_u64_u32 v[22:23], s[44:45], v214, s85, v[6:7]
	v_mad_u64_u32 v[24:25], s[44:45], v217, s85, v[6:7]
	v_mad_u64_u32 v[26:27], s[44:45], v216, s85, v[6:7]
	v_mad_u64_u32 v[28:29], s[44:45], v219, s85, v[6:7]
	v_mad_u64_u32 v[30:31], s[44:45], v218, s85, v[6:7]
	v_mad_u64_u32 v[32:33], s[44:45], v221, s85, v[6:7]
	v_mad_u64_u32 v[34:35], s[44:45], v220, s85, v[6:7]
	v_mad_u64_u32 v[36:37], s[44:45], v223, s85, v[6:7]
	v_mad_u64_u32 v[40:41], s[44:45], v222, s85, v[6:7]
	v_mad_u64_u32 v[42:43], s[44:45], v225, s85, v[6:7]
	v_mad_u64_u32 v[44:45], s[44:45], v224, s85, v[6:7]
	v_mad_u64_u32 v[46:47], s[44:45], v227, s85, v[6:7]
	v_mad_u64_u32 v[48:49], s[44:45], v226, s85, v[6:7]
	v_mad_u64_u32 v[50:51], s[44:45], v229, s85, v[6:7]
	v_mad_u64_u32 v[52:53], s[44:45], v228, s85, v[6:7]
	s_waitcnt vmcnt(31)
; __device__ __forceinline__ unsigned cvt_pk_bf16(float lo, float hi) { unsigned r; asm volatile("v_cvt_pk_bf16_f32 %0, %1, %2" : "=v"(r) : "v"(lo), "v"(hi)); return r; }
; #define LAS __attribute__((address_space(3)))
; #define LDS_WAIT() asm volatile("s_waitcnt lgkmcnt(0)" ::: "memory")
;     ...
;     for (int i = 0; i < 32; ++i) { const int kk = 2 * i + (lane >> 5); scr[kk * 33 + (lane & 31)] = W[(size_t)(k0 + kk) * N + n0 + (lane & 31)]; }
;     LDS_WAIT(); asm volatile("" ::: "memory");
;     const int c = lane & 7;
; #pragma unroll
;     for (int j = 0; j < 4; ++j) { const int n = (lane >> 3) + 8 * j; const LAS float* s = scr + (8 * c) * 33 + n;
;         u32x4 o; o.x = cvt_pk_bf16(s[0 * 33], s[1 * 33]); o.y = cvt_pk_bf16(s[2 * 33], s[3 * 33]); o.z = cvt_pk_bf16(s[4 * 33], s[5 * 33]); o.w = cvt_pk_bf16(s[6 * 33], s[7 * 33]);
;         *(u32x4*)(WT + (size_t)(dn0 + n) * ldo + koff + k0 + 8 * c) = o; }
	ds_write_b32 v16, v21
	s_waitcnt vmcnt(30)
	ds_write_b32 v22, v39
	s_waitcnt vmcnt(29)
	ds_write_b32 v24, v54
	s_waitcnt vmcnt(28)
	ds_write_b32 v26, v55
	s_waitcnt vmcnt(27)
	ds_write_b32 v28, v56
	s_waitcnt vmcnt(26)
	ds_write_b32 v30, v57
	s_waitcnt vmcnt(25)
	ds_write_b32 v32, v58
	s_waitcnt vmcnt(24)
	ds_write_b32 v34, v59
	s_waitcnt vmcnt(23)
	ds_write_b32 v36, v60
	s_waitcnt vmcnt(22)
	ds_write_b32 v40, v61
	s_waitcnt vmcnt(21)
	ds_write_b32 v42, v62
	s_waitcnt vmcnt(20)
	ds_write_b32 v44, v63
	s_waitcnt vmcnt(19)
	ds_write_b32 v46, v64
	s_waitcnt vmcnt(18)
	ds_write_b32 v48, v65
	s_waitcnt vmcnt(17)
	ds_write_b32 v50, v66
	s_waitcnt vmcnt(16)
	ds_write_b32 v52, v67
	v_mad_u64_u32 v[94:95], s[44:45], v157, s85, v[6:7]
	v_mad_u64_u32 v[98:99], s[44:45], v150, s85, v[6:7]
	v_mad_u64_u32 v[100:101], s[44:45], v159, s85, v[6:7]
	v_mad_u64_u32 v[102:103], s[44:45], v152, s85, v[6:7]
	v_mad_u64_u32 v[104:105], s[44:45], v161, s85, v[6:7]
	v_mad_u64_u32 v[106:107], s[44:45], v154, s85, v[6:7]
	v_mad_u64_u32 v[108:109], s[44:45], v163, s85, v[6:7]
	v_mad_u64_u32 v[110:111], s[44:45], v156, s85, v[6:7]
	v_mad_u64_u32 v[112:113], s[44:45], v165, s85, v[6:7]
	v_mad_u64_u32 v[116:117], s[44:45], v158, s85, v[6:7]
	v_mad_u64_u32 v[118:119], s[44:45], v167, s85, v[6:7]
	v_mad_u64_u32 v[120:121], s[44:45], v160, s85, v[6:7]
	v_mad_u64_u32 v[122:123], s[44:45], v169, s85, v[6:7]
	v_mad_u64_u32 v[124:125], s[44:45], v162, s85, v[6:7]
	v_mad_u64_u32 v[126:127], s[44:45], v183, s85, v[6:7]
	v_mad_u64_u32 v[128:129], s[44:45], v164, s85, v[6:7]
	s_waitcnt vmcnt(15)
	ds_write_b32 v94, v97
	s_waitcnt vmcnt(14)
	ds_write_b32 v98, v115
	s_waitcnt vmcnt(13)
	ds_write_b32 v100, v96
	s_waitcnt vmcnt(12)
	ds_write_b32 v102, v131
	s_waitcnt vmcnt(11)
	ds_write_b32 v104, v114
	s_waitcnt vmcnt(10)
	ds_write_b32 v106, v133
	s_waitcnt vmcnt(9)
	ds_write_b32 v108, v130
	s_waitcnt vmcnt(8)
	ds_write_b32 v110, v135
	s_waitcnt vmcnt(7)
	ds_write_b32 v112, v132
	s_waitcnt vmcnt(6)
	ds_write_b32 v116, v137
	s_waitcnt vmcnt(5)
	ds_write_b32 v118, v134
	s_waitcnt vmcnt(4)
	ds_write_b32 v120, v151
	s_waitcnt vmcnt(3)
	ds_write_b32 v122, v136
	s_waitcnt vmcnt(2)
	ds_write_b32 v124, v153
	s_waitcnt vmcnt(1)
	ds_write_b32 v126, v138
	s_waitcnt vmcnt(0)
	ds_write_b32 v128, v155
	s_waitcnt lgkmcnt(0)
	s_mul_hi_i32 s2, s0, 0x3100000
	s_mul_i32 s0, s0, 0x3100000
	s_add_u32 s3, s91, s0
	ds_read2_b32 v[14:15], v9 offset1:33
	s_addc_u32 s2, s93, s2
	s_waitcnt lgkmcnt(0)
	v_cvt_pk_bf16_f32 v14, v14, v15
	ds_read2_b32 v[16:17], v9 offset0:66 offset1:99
	s_cmpk_lt_i32 s1, 0x64
	s_waitcnt lgkmcnt(0)
	v_cvt_pk_bf16_f32 v15, v16, v17
	ds_read2_b32 v[16:17], v9 offset0:132 offset1:165
	s_cselect_b32 s0, 0, 0x80
	s_ashr_i32 s39, s38, 31
	s_add_i32 s40, s0, s40
	s_waitcnt lgkmcnt(0)
	v_cvt_pk_bf16_f32 v16, v16, v17
	ds_read2_b32 v[22:23], v9 offset0:198 offset1:231
	s_lshl_b64 s[0:1], s[38:39], 1
	s_add_u32 s0, s3, s0
	s_waitcnt lgkmcnt(0)
	v_cvt_pk_bf16_f32 v17, v22, v23
	v_or_b32_e32 v22, s40, v7
	v_lshlrev_b32_e32 v0, 1, v8
	s_addc_u32 s1, s2, s1
	v_ashrrev_i32_e32 v23, 31, v22
	v_lshl_add_u64 v[24:25], s[0:1], 0, v[0:1]
	v_lshlrev_b64 v[22:23], 12, v[22:23]
	ds_read2_b32 v[26:27], v9 offset0:8 offset1:41
	v_lshl_add_u64 v[22:23], v[24:25], 0, v[22:23]
	global_store_dwordx4 v[22:23], v[14:17], off sc1
	s_mov_b32 s48, 0x3a000000
	s_waitcnt lgkmcnt(0)
	v_cvt_pk_bf16_f32 v14, v26, v27
	v_or_b32_e32 v26, s40, v18
	v_ashrrev_i32_e32 v27, 31, v26
	ds_read2_b32 v[16:17], v9 offset0:74 offset1:107
	v_lshlrev_b64 v[26:27], 12, v[26:27]
	s_waitcnt lgkmcnt(0)
	v_cvt_pk_bf16_f32 v15, v16, v17
	ds_read2_b32 v[16:17], v9 offset0:140 offset1:173
	v_lshl_add_u64 v[26:27], v[24:25], 0, v[26:27]
	s_waitcnt lgkmcnt(0)
	v_cvt_pk_bf16_f32 v16, v16, v17
	ds_read2_b32 v[22:23], v9 offset0:206 offset1:239
	s_waitcnt lgkmcnt(0)
	v_cvt_pk_bf16_f32 v17, v22, v23
	global_store_dwordx4 v[26:27], v[14:17], off sc1
	v_or_b32_e32 v26, s40, v19
	ds_read2_b32 v[22:23], v9 offset0:16 offset1:49
	s_waitcnt lgkmcnt(0)
	v_cvt_pk_bf16_f32 v14, v22, v23
	ds_read2_b32 v[16:17], v9 offset0:82 offset1:115
	v_ashrrev_i32_e32 v27, 31, v26
	s_waitcnt lgkmcnt(0)
	v_cvt_pk_bf16_f32 v15, v16, v17
	ds_read2_b32 v[16:17], v9 offset0:148 offset1:181
	v_lshlrev_b64 v[26:27], 12, v[26:27]
	s_waitcnt lgkmcnt(0)
	v_cvt_pk_bf16_f32 v16, v16, v17
	ds_read2_b32 v[22:23], v9 offset0:214 offset1:247
	s_waitcnt lgkmcnt(0)
	v_cvt_pk_bf16_f32 v17, v22, v23
	v_lshl_add_u64 v[26:27], v[24:25], 0, v[26:27]
	ds_read2_b32 v[22:23], v9 offset0:24 offset1:57
	global_store_dwordx4 v[26:27], v[14:17], off sc1
	v_or_b32_e32 v26, s40, v20
	v_ashrrev_i32_e32 v27, 31, v26
	s_waitcnt lgkmcnt(0)
	v_cvt_pk_bf16_f32 v14, v22, v23
	ds_read2_b32 v[16:17], v9 offset0:90 offset1:123
	s_waitcnt lgkmcnt(0)
	v_cvt_pk_bf16_f32 v15, v16, v17
	ds_read2_b32 v[16:17], v9 offset0:156 offset1:189
	s_waitcnt lgkmcnt(0)
	v_cvt_pk_bf16_f32 v16, v16, v17
	ds_read2_b32 v[22:23], v9 offset0:222 offset1:255
	v_lshlrev_b64 v[26:27], 12, v[26:27]
	s_waitcnt lgkmcnt(0)
	v_cvt_pk_bf16_f32 v17, v22, v23
	v_lshl_add_u64 v[22:23], v[24:25], 0, v[26:27]
	global_store_dwordx4 v[22:23], v[14:17], off sc1
	s_waitcnt lgkmcnt(0)
	s_branch .LBB0_467
